# combo13 + attention loops: per-MFMA s_setprio toggling removed, one static s_setprio 1 for waves 4-7 per unit
# baseline (speedup 1.0000x reference)
.LBB0_701:
	s_mov_b32 m0, s4
	v_readlane_b32 s4, v251, 6
	s_cmpk_ge_u32 s4, 0x100
	s_mov_b32 s4, m0
	s_cbranch_scc0 .Lsp_skip_0
	s_setprio 1

.LBB0_709:
	v_lshrrev_b32_e32 v32, s33, v59
	v_and_b32_e32 v32, 1, v32
	s_lshl_b32 s6, s33, 6
	v_add_u32_e32 v79, s44, v120
	v_cmp_eq_u32_e64 s[44:45], 1, v32
	v_add_u32_e32 v77, v79, v141
	s_cmp_gt_i32 s6, s17
	v_cndmask_b32_e64 v96, 0, 1, s[44:45]
	s_cbranch_scc1 .LBB0_714
	v_cmp_ne_u32_e32 vcc, 0, v96
	s_cbranch_vccz .LBB0_714
	v_add_u32_e32 v36, v79, v123
	ds_read_b128 v[32:35], v36
	ds_read_b128 v[98:101], v36 offset:32
	ds_read_b128 v[146:149], v36 offset:64
	ds_read_b128 v[150:153], v36 offset:96
	s_waitcnt lgkmcnt(0)
	v_mfma_f32_32x32x16_bf16 v[32:47], v[32:35], v[80:83], 0
	v_mfma_f32_32x32x16_bf16 v[32:47], v[98:101], v[84:87], v[32:47]
	v_mfma_f32_32x32x16_bf16 v[32:47], v[146:149], v[88:91], v[32:47]
	v_mfma_f32_32x32x16_bf16 v[32:47], v[150:153], v[92:95], v[32:47]
	s_sub_i32 m0, s17, 62
	s_cmp_le_i32 s6, m0
	s_cbranch_scc0 .Lsel0_masked
	v_cndmask_b32_e64 v166, v212, 0, s[44:45]
	s_nop 7
	v_fma_f32 v119, v32, s28, v166
	v_fma_f32 v118, v33, s28, v166
	v_fma_f32 v103, v34, s28, v166
	v_fma_f32 v102, v35, s28, v166
	v_fma_f32 v101, v36, s28, v166
	v_fma_f32 v100, v37, s28, v166
	v_fma_f32 v99, v38, s28, v166
	v_fma_f32 v98, v39, s28, v166
	v_fma_f32 v97, v40, s28, v166
	v_fma_f32 v40, v41, s28, v166
	v_fma_f32 v39, v42, s28, v166
	v_fma_f32 v38, v43, s28, v166
	v_fma_f32 v37, v44, s28, v166
	v_fma_f32 v36, v45, s28, v166
	v_fma_f32 v35, v46, s28, v166
	v_fma_f32 v34, v47, s28, v166
	v_max_f32_e32 v43, v35, v34
	v_max_f32_e32 v32, v103, v102
	v_max_f32_e32 v33, v99, v98
	v_max_f32_e32 v41, v97, v40
	v_max_f32_e32 v42, v39, v38
	v_max3_f32 v43, v37, v36, v43
	v_max3_f32 v32, v119, v118, v32
	v_max3_f32 v33, v101, v100, v33
	v_max3_f32 v41, v41, v42, v43
	v_max3_f32 v32, v32, v33, v41
	s_branch .Lsel0_join

.LBB0_713:
	v_add_u32_e32 v196, v77, v122
	v_add_u32_e32 v197, 0x2000, v196
	ds_read2_b64 v[180:183], v197 offset0:128 offset1:130
	ds_read2_b64 v[184:187], v197 offset0:132 offset1:134
	v_add_u32_e32 v197, 0x3000, v196
	ds_read2_b64 v[188:191], v197 offset0:160 offset1:162
	ds_read2_b64 v[192:195], v197 offset0:164 offset1:166
	v_sub_f32_e32 v42, v119, v41
	v_exp_f32_e32 v42, v42
	v_sub_f32_e32 v44, v118, v41
	v_exp_f32_e32 v44, v44
	v_sub_f32_e32 v45, v103, v41
	v_exp_f32_e32 v45, v45
	v_sub_f32_e32 v46, v102, v41
	v_exp_f32_e32 v46, v46
	v_sub_f32_e32 v47, v101, v41
	v_add_f32_e32 v43, 0, v42
	v_exp_f32_e32 v47, v47
	v_sub_f32_e32 v78, v100, v41
	v_add_f32_e32 v43, v44, v43
	v_exp_f32_e32 v78, v78
	v_sub_f32_e32 v99, v99, v41
	v_add_f32_e32 v43, v45, v43
	v_exp_f32_e32 v99, v99
	v_sub_f32_e32 v98, v98, v41
	v_add_f32_e32 v43, v46, v43
	v_exp_f32_e32 v98, v98
	v_sub_f32_e32 v97, v97, v41
	v_add_f32_e32 v43, v47, v43
	v_exp_f32_e32 v97, v97
	v_sub_f32_e32 v40, v40, v41
	v_add_f32_e32 v43, v78, v43
	v_exp_f32_e32 v40, v40
	v_sub_f32_e32 v39, v39, v41
	v_add_f32_e32 v43, v99, v43
	v_exp_f32_e32 v39, v39
	v_sub_f32_e32 v38, v38, v41
	v_add_f32_e32 v43, v98, v43
	v_exp_f32_e32 v100, v38
	v_add_f32_e32 v43, v97, v43
	v_add_f32_e32 v43, v40, v43
	v_add_f32_e32 v43, v39, v43
	v_sub_f32_e32 v37, v37, v41
	v_add_f32_e32 v38, v100, v43
	v_exp_f32_e32 v43, v37
	v_sub_f32_e32 v36, v36, v41
	v_exp_f32_e32 v101, v36
	v_sub_f32_e32 v35, v35, v41
	v_exp_f32_e32 v102, v35
	v_sub_f32_e32 v34, v34, v41
	v_exp_f32_e32 v41, v34
	v_add_f32_e32 v37, v43, v38
	v_add_f32_e32 v36, v101, v37
	v_add_f32_e32 v35, v102, v36
	v_add_f32_e32 v103, v41, v35
	v_fmac_f32_e32 v103, v144, v32
	v_add_u32_e32 v32, v77, v122
	v_cvt_pk_bf16_f32 v35, v45, v46
	v_add_u32_e32 v46, 0x2000, v32
	v_cvt_pk_bf16_f32 v34, v42, v44
	v_cvt_pk_bf16_f32 v37, v99, v98
	v_cvt_pk_bf16_f32 v38, v97, v40
	v_cvt_pk_bf16_f32 v39, v39, v100
	v_cvt_pk_bf16_f32 v40, v43, v101
	v_cvt_pk_bf16_f32 v36, v47, v78
	v_cvt_pk_bf16_f32 v41, v102, v41
	s_waitcnt lgkmcnt(0)
	v_mfma_f32_32x32x16_bf16 v[16:31], v[180:183], v[34:37], v[16:31]
	v_mfma_f32_32x32x16_bf16 v[16:31], v[184:187], v[38:41], v[16:31]
	v_add_u32_e32 v32, 0x3000, v32
	s_waitcnt lgkmcnt(0)
	v_mfma_f32_32x32x16_bf16 v[0:15], v[188:191], v[34:37], v[0:15]
	v_mfma_f32_32x32x16_bf16 v[0:15], v[192:195], v[38:41], v[0:15]
	v_mov_b32_e32 v144, v103
	v_mov_b32_e32 v78, v33
.LBB0_714:
	s_or_b32 s6, s6, 32
	s_cmp_gt_i32 s6, s17
	s_cbranch_scc1 .LBB0_719
	v_cmp_ne_u32_e32 vcc, 0, v96
	s_cbranch_vccz .LBB0_719
	v_add_u32_e32 v36, v79, v123
	ds_read_b128 v[32:35], v36 offset:4608
	ds_read_b128 v[96:99], v36 offset:4640
	ds_read_b128 v[100:103], v36 offset:4672
	ds_read_b128 v[146:149], v36 offset:4704
	s_waitcnt lgkmcnt(0)
	v_mfma_f32_32x32x16_bf16 v[32:47], v[32:35], v[80:83], 0
	v_mfma_f32_32x32x16_bf16 v[32:47], v[96:99], v[84:87], v[32:47]
	v_mfma_f32_32x32x16_bf16 v[32:47], v[100:103], v[88:91], v[32:47]
	v_mfma_f32_32x32x16_bf16 v[32:47], v[146:149], v[92:95], v[32:47]
	s_sub_i32 m0, s17, 62
	s_cmp_le_i32 s6, m0
	s_cbranch_scc0 .Lsel1_masked
	v_cndmask_b32_e64 v166, v212, 0, s[44:45]
	s_nop 7
	v_fma_f32 v103, v32, s28, v166
	v_fma_f32 v102, v33, s28, v166
	v_fma_f32 v101, v34, s28, v166
	v_fma_f32 v100, v35, s28, v166
	v_fma_f32 v99, v36, s28, v166
	v_fma_f32 v98, v37, s28, v166
	v_fma_f32 v97, v38, s28, v166
	v_fma_f32 v96, v39, s28, v166
	v_fma_f32 v79, v40, s28, v166
	v_fma_f32 v40, v41, s28, v166
	v_fma_f32 v39, v42, s28, v166
	v_fma_f32 v38, v43, s28, v166
	v_fma_f32 v37, v44, s28, v166
	v_fma_f32 v36, v45, s28, v166
	v_fma_f32 v35, v46, s28, v166
	v_fma_f32 v34, v47, s28, v166
	v_max_f32_e32 v43, v35, v34
	v_max_f32_e32 v32, v101, v100
	v_max_f32_e32 v33, v97, v96
	v_max_f32_e32 v41, v79, v40
	v_max_f32_e32 v42, v39, v38
	v_max3_f32 v43, v37, v36, v43
	v_max3_f32 v32, v103, v102, v32
	v_max3_f32 v33, v99, v98, v33
	v_max3_f32 v41, v41, v42, v43
	v_max3_f32 v32, v32, v33, v41
	s_branch .Lsel1_join

.LBB0_718:
	v_add_u32_e32 v196, v77, v122
	v_add_u32_e32 v197, 0x2000, v196
	ds_read2_b64 v[180:183], v197 offset0:136 offset1:138
	ds_read2_b64 v[184:187], v197 offset0:140 offset1:142
	v_add_u32_e32 v197, 0x3000, v196
	ds_read2_b64 v[188:191], v197 offset0:168 offset1:170
	ds_read2_b64 v[192:195], v197 offset0:172 offset1:174
	v_sub_f32_e32 v42, v103, v41
	v_exp_f32_e32 v42, v42
	v_sub_f32_e32 v44, v102, v41
	v_exp_f32_e32 v44, v44
	v_sub_f32_e32 v45, v101, v41
	v_exp_f32_e32 v45, v45
	v_sub_f32_e32 v46, v100, v41
	v_exp_f32_e32 v46, v46
	v_sub_f32_e32 v47, v99, v41
	v_add_f32_e32 v43, 0, v42
	v_exp_f32_e32 v47, v47
	v_sub_f32_e32 v78, v98, v41
	v_add_f32_e32 v43, v44, v43
	v_exp_f32_e32 v78, v78
	v_sub_f32_e32 v97, v97, v41
	v_add_f32_e32 v43, v45, v43
	v_exp_f32_e32 v97, v97
	v_sub_f32_e32 v96, v96, v41
	v_add_f32_e32 v43, v46, v43
	v_exp_f32_e32 v96, v96
	v_sub_f32_e32 v79, v79, v41
	v_add_f32_e32 v43, v47, v43
	v_exp_f32_e32 v79, v79
	v_sub_f32_e32 v40, v40, v41
	v_add_f32_e32 v43, v78, v43
	v_exp_f32_e32 v40, v40
	v_sub_f32_e32 v39, v39, v41
	v_add_f32_e32 v43, v97, v43
	v_exp_f32_e32 v39, v39
	v_sub_f32_e32 v38, v38, v41
	v_add_f32_e32 v43, v96, v43
	v_exp_f32_e32 v98, v38
	v_add_f32_e32 v43, v79, v43
	v_add_f32_e32 v43, v40, v43
	v_add_f32_e32 v43, v39, v43
	v_sub_f32_e32 v37, v37, v41
	v_add_f32_e32 v38, v98, v43
	v_exp_f32_e32 v43, v37
	v_sub_f32_e32 v36, v36, v41
	v_exp_f32_e32 v99, v36
	v_sub_f32_e32 v35, v35, v41
	v_exp_f32_e32 v100, v35
	v_sub_f32_e32 v34, v34, v41
	v_exp_f32_e32 v41, v34
	v_add_f32_e32 v37, v43, v38
	v_add_f32_e32 v36, v99, v37
	v_add_f32_e32 v35, v100, v36
	v_add_f32_e32 v101, v41, v35
	v_fmac_f32_e32 v101, v144, v32
	v_add_u32_e32 v32, v77, v122
	v_cvt_pk_bf16_f32 v35, v45, v46
	v_add_u32_e32 v46, 0x2000, v32
	v_cvt_pk_bf16_f32 v34, v42, v44
	v_cvt_pk_bf16_f32 v37, v97, v96
	v_cvt_pk_bf16_f32 v38, v79, v40
	v_cvt_pk_bf16_f32 v39, v39, v98
	v_cvt_pk_bf16_f32 v40, v43, v99
	v_cvt_pk_bf16_f32 v36, v47, v78
	v_cvt_pk_bf16_f32 v41, v100, v41
	s_waitcnt lgkmcnt(0)
	v_mfma_f32_32x32x16_bf16 v[16:31], v[180:183], v[34:37], v[16:31]
	v_mfma_f32_32x32x16_bf16 v[16:31], v[184:187], v[38:41], v[16:31]
	v_add_u32_e32 v32, 0x3000, v32
	s_waitcnt lgkmcnt(0)
	v_mfma_f32_32x32x16_bf16 v[0:15], v[188:191], v[34:37], v[0:15]
	v_mfma_f32_32x32x16_bf16 v[0:15], v[192:195], v[38:41], v[0:15]
	v_mov_b32_e32 v144, v101
	v_mov_b32_e32 v78, v33

.LBB0_728:
	s_cmp_le_i32 s6, s17
	v_add_u32_e32 v64, s18, v120
	s_cselect_b64 s[20:21], -1, 0
	s_add_i32 s18, s6, 31
	s_cmp_ge_i32 s18, s19
	s_cselect_b64 s[38:39], -1, 0
	s_and_b64 s[20:21], s[20:21], s[38:39]
	v_add_u32_e32 v150, v64, v141
	s_andn2_b64 vcc, exec, s[20:21]
	v_add_u32_e32 v152, v64, v123
	s_cbranch_vccnz .LBB0_732
	ds_read_b128 v[64:67], v152
	ds_read_b128 v[154:157], v152 offset:32
	ds_read_b128 v[158:161], v152 offset:64
	ds_read_b128 v[162:165], v152 offset:96
	s_waitcnt lgkmcnt(0)
	v_mfma_f32_32x32x16_bf16 v[64:79], v[64:67], v[80:83], 0
	v_mfma_f32_32x32x16_bf16 v[64:79], v[154:157], v[84:87], v[64:79]
	v_mfma_f32_32x32x16_bf16 v[64:79], v[158:161], v[88:91], v[64:79]
	v_mfma_f32_32x32x16_bf16 v[64:79], v[162:165], v[92:95], v[64:79]
	s_nop 10
	s_sub_i32 m0, s17, 62
	s_cmp_le_i32 s6, m0
	s_cbranch_scc0 .Lwin0_masked
	s_add_i32 m0, s19, 31
	s_cmp_ge_i32 s6, m0
	s_cbranch_scc0 .Lwin0_masked
	v_mul_f32_e32 v162, 0x3e38aa3b, v64
	v_mul_f32_e32 v161, 0x3e38aa3b, v65
	v_mul_f32_e32 v160, 0x3e38aa3b, v66
	v_mul_f32_e32 v159, 0x3e38aa3b, v67
	v_mul_f32_e32 v158, 0x3e38aa3b, v68
	v_mul_f32_e32 v157, 0x3e38aa3b, v69
	v_mul_f32_e32 v156, 0x3e38aa3b, v70
	v_mul_f32_e32 v155, 0x3e38aa3b, v71
	v_max_f32_e32 v69, v156, v155
	v_mul_f32_e32 v154, 0x3e38aa3b, v72
	v_max3_f32 v69, v158, v157, v69
	v_mul_f32_e32 v72, 0x3e38aa3b, v73
	v_max_f32_e32 v73, v154, v72
	v_mul_f32_e32 v71, 0x3e38aa3b, v74
	v_mul_f32_e32 v70, 0x3e38aa3b, v75
	v_max_f32_e32 v74, v71, v70
	v_mul_f32_e32 v68, 0x3e38aa3b, v76
	v_mul_f32_e32 v67, 0x3e38aa3b, v77
	v_mul_f32_e32 v66, 0x3e38aa3b, v78
	v_max_f32_e32 v64, v160, v159
	v_max3_f32 v64, v162, v161, v64
	v_mul_f32_e32 v65, 0x3e38aa3b, v79
	v_max_f32_e32 v75, v66, v65
	v_max3_f32 v75, v68, v67, v75
	v_max3_f32 v73, v73, v74, v75
	v_max3_f32 v64, v64, v69, v73
	s_branch .Lwin0_join

.LBB0_731:
	v_add_u32_e32 v196, v150, v122
	v_add_u32_e32 v197, 0x2000, v196
	ds_read2_b64 v[180:183], v197 offset0:128 offset1:130
	ds_read2_b64 v[184:187], v197 offset0:132 offset1:134
	v_add_u32_e32 v197, 0x3000, v196
	ds_read2_b64 v[188:191], v197 offset0:160 offset1:162
	ds_read2_b64 v[192:195], v197 offset0:164 offset1:166
	v_sub_f32_e32 v73, v162, v69
	v_exp_f32_e32 v73, v73
	v_sub_f32_e32 v75, v161, v69
	v_exp_f32_e32 v75, v75
	v_sub_f32_e32 v76, v160, v69
	v_exp_f32_e32 v76, v76
	v_sub_f32_e32 v77, v159, v69
	v_exp_f32_e32 v77, v77
	v_sub_f32_e32 v78, v158, v69
	v_add_f32_e32 v74, 0, v73
	v_exp_f32_e32 v78, v78
	v_sub_f32_e32 v79, v157, v69
	v_add_f32_e32 v74, v75, v74
	v_exp_f32_e32 v79, v79
	v_sub_f32_e32 v151, v156, v69
	v_add_f32_e32 v74, v76, v74
	v_exp_f32_e32 v151, v151
	v_sub_f32_e32 v155, v155, v69
	v_add_f32_e32 v74, v77, v74
	v_exp_f32_e32 v155, v155
	v_sub_f32_e32 v154, v154, v69
	v_add_f32_e32 v74, v78, v74
	v_exp_f32_e32 v154, v154
	v_sub_f32_e32 v72, v72, v69
	v_add_f32_e32 v74, v79, v74
	v_exp_f32_e32 v72, v72
	v_sub_f32_e32 v71, v71, v69
	v_add_f32_e32 v74, v151, v74
	v_exp_f32_e32 v71, v71
	v_sub_f32_e32 v70, v70, v69
	v_add_f32_e32 v74, v155, v74
	v_exp_f32_e32 v70, v70
	v_sub_f32_e32 v68, v68, v69
	v_add_f32_e32 v74, v154, v74
	v_exp_f32_e32 v156, v68
	v_add_f32_e32 v74, v72, v74
	v_add_f32_e32 v74, v71, v74
	v_add_f32_e32 v74, v70, v74
	v_sub_f32_e32 v67, v67, v69
	v_add_f32_e32 v68, v156, v74
	v_exp_f32_e32 v74, v67
	v_sub_f32_e32 v66, v66, v69
	v_exp_f32_e32 v157, v66
	v_sub_f32_e32 v65, v65, v69
	v_exp_f32_e32 v158, v65
	v_add_f32_e32 v67, v74, v68
	v_add_f32_e32 v66, v157, v67
	v_cvt_pk_bf16_f32 v65, v76, v77
	v_add_f32_e32 v159, v158, v66
	v_fmac_f32_e32 v159, v149, v64
	v_add_u32_e32 v149, v150, v122
	v_add_u32_e32 v76, 0x2000, v149
	v_cvt_pk_bf16_f32 v64, v73, v75
	v_cvt_pk_bf16_f32 v66, v78, v79
	v_cvt_pk_bf16_f32 v68, v154, v72
	v_cvt_pk_bf16_f32 v69, v71, v70
	v_cvt_pk_bf16_f32 v70, v156, v74
	v_cvt_pk_bf16_f32 v67, v151, v155
	v_cvt_pk_bf16_f32 v71, v157, v158
	s_waitcnt lgkmcnt(0)
	v_mfma_f32_32x32x16_bf16 v[48:63], v[180:183], v[64:67], v[48:63]
	v_mfma_f32_32x32x16_bf16 v[48:63], v[184:187], v[68:71], v[48:63]
	s_waitcnt lgkmcnt(0)
	v_mfma_f32_32x32x16_bf16 v[32:47], v[188:191], v[64:67], v[32:47]
	v_mfma_f32_32x32x16_bf16 v[32:47], v[192:195], v[68:71], v[32:47]
	v_mov_b32_e32 v149, v159
	s_branch .LBB0_733

.LBB0_733:
	s_add_i32 s18, s6, 32
	s_cmp_le_i32 s18, s17
	s_cselect_b64 s[20:21], -1, 0
	s_add_i32 s18, s6, 63
	s_cmp_ge_i32 s18, s19
	s_cselect_b64 s[38:39], -1, 0
	s_and_b64 s[20:21], s[20:21], s[38:39]
	s_andn2_b64 vcc, exec, s[20:21]
	s_cbranch_vccnz .LBB0_724
	ds_read_b128 v[64:67], v152 offset:4608
	ds_read_b128 v[154:157], v152 offset:4640
	ds_read_b128 v[158:161], v152 offset:4672
	ds_read_b128 v[162:165], v152 offset:4704
	s_waitcnt lgkmcnt(0)
	v_mfma_f32_32x32x16_bf16 v[64:79], v[64:67], v[80:83], 0
	v_mfma_f32_32x32x16_bf16 v[64:79], v[154:157], v[84:87], v[64:79]
	v_mfma_f32_32x32x16_bf16 v[64:79], v[158:161], v[88:91], v[64:79]
	v_mfma_f32_32x32x16_bf16 v[64:79], v[162:165], v[92:95], v[64:79]
	v_subrev_u32_e32 v151, 32, v147
	s_nop 9
	s_sub_i32 m0, s17, 94
	s_cmp_le_i32 s6, m0
	s_cbranch_scc0 .Lwin1_masked
	s_add_i32 m0, s19, -1
	s_cmp_ge_i32 s6, m0
	s_cbranch_scc0 .Lwin1_masked
	v_mul_f32_e32 v161, 0x3e38aa3b, v64
	v_mul_f32_e32 v160, 0x3e38aa3b, v65
	v_mul_f32_e32 v159, 0x3e38aa3b, v66
	v_mul_f32_e32 v158, 0x3e38aa3b, v67
	v_mul_f32_e32 v157, 0x3e38aa3b, v68
	v_mul_f32_e32 v156, 0x3e38aa3b, v69
	v_mul_f32_e32 v155, 0x3e38aa3b, v70
	v_mul_f32_e32 v154, 0x3e38aa3b, v71
	v_max_f32_e32 v69, v155, v154
	v_mul_f32_e32 v152, 0x3e38aa3b, v72
	v_max3_f32 v69, v157, v156, v69
	v_mul_f32_e32 v72, 0x3e38aa3b, v73
	v_max_f32_e32 v73, v152, v72
	v_mul_f32_e32 v71, 0x3e38aa3b, v74
	v_mul_f32_e32 v70, 0x3e38aa3b, v75
	v_max_f32_e32 v74, v71, v70
	v_mul_f32_e32 v68, 0x3e38aa3b, v76
	v_mul_f32_e32 v67, 0x3e38aa3b, v77
	v_mul_f32_e32 v66, 0x3e38aa3b, v78
	v_max_f32_e32 v64, v159, v158
	v_max3_f32 v64, v161, v160, v64
	v_mul_f32_e32 v65, 0x3e38aa3b, v79
	v_max_f32_e32 v75, v66, v65
	v_max3_f32 v75, v68, v67, v75
	v_max3_f32 v73, v73, v74, v75
	v_max3_f32 v64, v64, v69, v73
	s_branch .Lwin1_join

.LBB0_736:
	v_add_u32_e32 v196, v150, v122
	v_add_u32_e32 v197, 0x2000, v196
	ds_read2_b64 v[180:183], v197 offset0:136 offset1:138
	ds_read2_b64 v[184:187], v197 offset0:140 offset1:142
	v_add_u32_e32 v197, 0x3000, v196
	ds_read2_b64 v[188:191], v197 offset0:168 offset1:170
	ds_read2_b64 v[192:195], v197 offset0:172 offset1:174
	v_sub_f32_e32 v73, v161, v69
	v_exp_f32_e32 v73, v73
	v_sub_f32_e32 v75, v160, v69
	v_exp_f32_e32 v75, v75
	v_sub_f32_e32 v76, v159, v69
	v_exp_f32_e32 v76, v76
	v_sub_f32_e32 v77, v158, v69
	v_exp_f32_e32 v77, v77
	v_sub_f32_e32 v78, v157, v69
	v_add_f32_e32 v74, 0, v73
	v_exp_f32_e32 v78, v78
	v_sub_f32_e32 v79, v156, v69
	v_add_f32_e32 v74, v75, v74
	v_exp_f32_e32 v79, v79
	v_sub_f32_e32 v153, v155, v69
	v_add_f32_e32 v74, v76, v74
	v_exp_f32_e32 v153, v153
	v_sub_f32_e32 v154, v154, v69
	v_add_f32_e32 v74, v77, v74
	v_exp_f32_e32 v154, v154
	v_sub_f32_e32 v152, v152, v69
	v_add_f32_e32 v74, v78, v74
	v_exp_f32_e32 v152, v152
	v_sub_f32_e32 v72, v72, v69
	v_add_f32_e32 v74, v79, v74
	v_exp_f32_e32 v72, v72
	v_sub_f32_e32 v71, v71, v69
	v_add_f32_e32 v74, v153, v74
	v_exp_f32_e32 v71, v71
	v_sub_f32_e32 v70, v70, v69
	v_add_f32_e32 v74, v154, v74
	v_exp_f32_e32 v70, v70
	v_sub_f32_e32 v68, v68, v69
	v_add_f32_e32 v74, v152, v74
	v_exp_f32_e32 v155, v68
	v_add_f32_e32 v74, v72, v74
	v_add_f32_e32 v74, v71, v74
	v_add_f32_e32 v74, v70, v74
	v_sub_f32_e32 v67, v67, v69
	v_add_f32_e32 v68, v155, v74
	v_exp_f32_e32 v74, v67
	v_sub_f32_e32 v66, v66, v69
	v_exp_f32_e32 v156, v66
	v_sub_f32_e32 v65, v65, v69
	v_exp_f32_e32 v157, v65
	v_add_f32_e32 v67, v74, v68
	v_add_f32_e32 v66, v156, v67
	v_cvt_pk_bf16_f32 v65, v76, v77
	v_add_f32_e32 v158, v157, v66
	v_fmac_f32_e32 v158, v149, v64
	v_add_u32_e32 v149, v150, v122
	v_add_u32_e32 v76, 0x2000, v149
	v_cvt_pk_bf16_f32 v64, v73, v75
	v_cvt_pk_bf16_f32 v66, v78, v79
	v_cvt_pk_bf16_f32 v68, v152, v72
	v_cvt_pk_bf16_f32 v69, v71, v70
	v_cvt_pk_bf16_f32 v70, v155, v74
	v_cvt_pk_bf16_f32 v67, v153, v154
	v_cvt_pk_bf16_f32 v71, v156, v157
	s_waitcnt lgkmcnt(0)
	v_mfma_f32_32x32x16_bf16 v[48:63], v[180:183], v[64:67], v[48:63]
	v_mfma_f32_32x32x16_bf16 v[48:63], v[184:187], v[68:71], v[48:63]
	s_waitcnt lgkmcnt(0)
	v_mfma_f32_32x32x16_bf16 v[32:47], v[188:191], v[64:67], v[32:47]
	v_mfma_f32_32x32x16_bf16 v[32:47], v[192:195], v[68:71], v[32:47]
	v_mov_b32_e32 v149, v158
	s_branch .LBB0_725

.LBB0_750:
	s_sub_i32 s6, s92, 32
	v_add_u32_e32 v32, s18, v97
	v_add_u32_e32 v99, v32, v118
	s_cmp_gt_i32 s6, s86
	v_add_u32_e32 v121, v32, v112
	v_add_u32_e32 v105, s89, v119
	s_cbranch_scc1 .LBB0_766
	ds_read_b128 v[32:35], v121
	ds_read_b128 v[36:39], v121 offset:32
	ds_read_b128 v[40:43], v121 offset:64
	ds_read_b128 v[44:47], v121 offset:96
	s_waitcnt lgkmcnt(0)
	v_mfma_f32_32x32x16_bf16 v[48:63], v[32:35], v[64:67], 0
	v_mfma_f32_32x32x16_bf16 v[48:63], v[36:39], v[68:71], v[48:63]
	v_mfma_f32_32x32x16_bf16 v[48:63], v[40:43], v[72:75], v[48:63]
	v_mfma_f32_32x32x16_bf16 v[48:63], v[44:47], v[76:79], v[48:63]
	s_sub_i32 s6, s89, 62
	v_subrev_u32_e32 v122, 31, v105
	s_cmpk_lt_i32 s6, 0x201
	s_mov_b64 s[18:19], -1
	s_cbranch_scc0 .LBB0_761
	s_cmpk_gt_i32 s6, 0x80
	s_cselect_b64 s[18:19], -1, 0
	s_cmpk_lt_i32 s89, 0x201
	s_cselect_b64 s[54:55], -1, 0
	s_and_b64 s[18:19], s[18:19], s[54:55]
	s_andn2_b64 vcc, exec, s[18:19]
	s_mov_b64 s[18:19], -1
	s_cbranch_vccz .LBB0_758
	s_cmp_gt_i32 s6, -1
	s_cselect_b64 s[18:19], -1, 0
	s_cmpk_lt_i32 s89, 0x81
	s_cselect_b64 s[54:55], -1, 0
	s_and_b64 s[54:55], s[18:19], s[54:55]
	s_mov_b64 s[18:19], -1
	s_and_b64 vcc, exec, s[54:55]
	s_cbranch_vccnz .LBB0_755
	s_movk_i32 s6, 0x81
	v_cmp_gt_i32_e32 vcc, s6, v122
	s_movk_i32 s6, 0x201
	v_and_b32_e32 v39, 15, v122
	v_cndmask_b32_e64 v32, 0, 1, vcc
	v_cmp_gt_i32_e32 vcc, s6, v122
	s_and_b64 s[18:19], s[42:43], vcc
	v_cndmask_b32_e64 v33, 0, 1, s[18:19]
	v_cmp_eq_u32_e32 vcc, 0, v39
	s_movk_i32 s6, 0x82
	s_nop 0
	v_addc_co_u32_e64 v32, s[54:55], v33, v32, vcc
	v_cmp_eq_u32_e64 s[54:55], 2, v32
	v_cmp_ne_u32_e64 s[56:57], 0, v32
	s_nop 0
	v_cndmask_b32_e64 v33, 0, 1.0, s[54:55]
	v_cmp_gt_u32_e64 s[54:55], 3, v32
	s_nop 1
	v_cndmask_b32_e64 v33, v214, v33, s[54:55]
	v_cmp_lt_i32_e64 s[54:55], -1, v122
	v_fmac_f32_e32 v33, 0x3e38aa3b, v48
	s_and_b64 s[54:55], s[54:55], s[56:57]
	v_cndmask_b32_e64 v32, v212, v33, s[54:55]
	v_cmp_gt_i32_e64 s[54:55], s6, v122
	s_movk_i32 s6, 0x202
	s_nop 0
	v_cndmask_b32_e64 v33, 0, 1, s[54:55]
	v_cmp_gt_i32_e64 s[54:55], s6, v122
	s_and_b64 s[18:19], s[44:45], s[54:55]
	v_cndmask_b32_e64 v34, 0, 1, s[18:19]
	v_cmp_eq_u32_e64 s[54:55], 1, v39
	s_movk_i32 s6, 0x83
	s_nop 0
	v_addc_co_u32_e64 v33, s[56:57], v34, v33, s[54:55]
	v_cmp_eq_u32_e64 s[56:57], 2, v33
	v_cmp_ne_u32_e64 s[58:59], 0, v33
	s_nop 0
	v_cndmask_b32_e64 v34, 0, 1.0, s[56:57]
	v_cmp_gt_u32_e64 s[56:57], 3, v33
	s_nop 1
	v_cndmask_b32_e64 v34, v214, v34, s[56:57]
	v_cmp_lt_i32_e64 s[56:57], 0, v122
	v_fmac_f32_e32 v34, 0x3e38aa3b, v49
	s_and_b64 s[56:57], s[56:57], s[58:59]
	v_cndmask_b32_e64 v33, v212, v34, s[56:57]
	v_cmp_gt_i32_e64 s[56:57], s6, v122
	s_movk_i32 s6, 0x203
	s_nop 0
	v_cndmask_b32_e64 v34, 0, 1, s[56:57]
	v_cmp_gt_i32_e64 s[56:57], s6, v122
	s_and_b64 s[18:19], s[46:47], s[56:57]
	v_cndmask_b32_e64 v35, 0, 1, s[18:19]
	v_cmp_eq_u32_e64 s[56:57], 2, v39
	s_movk_i32 s6, 0x84
	s_nop 0
	v_addc_co_u32_e64 v34, s[58:59], v35, v34, s[56:57]
	v_cmp_eq_u32_e64 s[58:59], 2, v34
	v_cmp_ne_u32_e64 s[60:61], 0, v34
	s_nop 0
	v_cndmask_b32_e64 v35, 0, 1.0, s[58:59]
	v_cmp_gt_u32_e64 s[58:59], 3, v34
	s_nop 1
	v_cndmask_b32_e64 v35, v214, v35, s[58:59]
	v_cmp_lt_i32_e64 s[58:59], 1, v122
	v_fmac_f32_e32 v35, 0x3e38aa3b, v50
	s_and_b64 s[58:59], s[58:59], s[60:61]
	v_cndmask_b32_e64 v34, v212, v35, s[58:59]
	v_cmp_gt_i32_e64 s[58:59], s6, v122
	s_movk_i32 s6, 0x204
	s_nop 0
	v_cndmask_b32_e64 v35, 0, 1, s[58:59]
	v_cmp_gt_i32_e64 s[58:59], s6, v122
	s_and_b64 s[18:19], s[48:49], s[58:59]
	v_cndmask_b32_e64 v36, 0, 1, s[18:19]
	v_cmp_eq_u32_e64 s[58:59], 3, v39
	s_movk_i32 s6, 0x89
	s_nop 0
	v_addc_co_u32_e64 v35, s[60:61], v36, v35, s[58:59]
	v_cmp_eq_u32_e64 s[60:61], 2, v35
	v_cmp_ne_u32_e64 s[62:63], 0, v35
	s_nop 0
	v_cndmask_b32_e64 v36, 0, 1.0, s[60:61]
	v_cmp_gt_u32_e64 s[60:61], 3, v35
	s_nop 1
	v_cndmask_b32_e64 v36, v214, v36, s[60:61]
	v_cmp_lt_i32_e64 s[60:61], 2, v122
	v_fmac_f32_e32 v36, 0x3e38aa3b, v51
	s_and_b64 s[60:61], s[60:61], s[62:63]
	v_cndmask_b32_e64 v35, v212, v36, s[60:61]
	v_cmp_gt_i32_e64 s[60:61], s6, v122
	s_movk_i32 s6, 0x209
	s_nop 0
	v_cndmask_b32_e64 v36, 0, 1, s[60:61]
	v_cmp_gt_i32_e64 s[60:61], s6, v122
	s_and_b64 s[18:19], s[42:43], s[60:61]
	v_cndmask_b32_e64 v37, 0, 1, s[18:19]
	v_cmp_eq_u32_e64 s[60:61], 8, v39
	s_movk_i32 s6, 0x8a
	s_nop 0
	v_addc_co_u32_e64 v36, s[62:63], v37, v36, s[60:61]
	v_cmp_eq_u32_e64 s[62:63], 2, v36
	v_cmp_ne_u32_e64 s[64:65], 0, v36
	s_nop 0
	v_cndmask_b32_e64 v37, 0, 1.0, s[62:63]
	v_cmp_gt_u32_e64 s[62:63], 3, v36
	s_nop 1
	v_cndmask_b32_e64 v37, v214, v37, s[62:63]
	v_cmp_lt_i32_e64 s[62:63], 7, v122
	v_fmac_f32_e32 v37, 0x3e38aa3b, v52
	s_and_b64 s[62:63], s[62:63], s[64:65]
	v_cndmask_b32_e64 v36, v212, v37, s[62:63]
	v_cmp_gt_i32_e64 s[62:63], s6, v122
	s_movk_i32 s6, 0x20a
	s_nop 0
	v_cndmask_b32_e64 v37, 0, 1, s[62:63]
	v_cmp_gt_i32_e64 s[62:63], s6, v122
	s_and_b64 s[18:19], s[44:45], s[62:63]
	v_cndmask_b32_e64 v38, 0, 1, s[18:19]
	v_cmp_eq_u32_e64 s[62:63], 9, v39
	s_movk_i32 s6, 0x8b
	s_nop 0
	v_addc_co_u32_e64 v37, s[64:65], v38, v37, s[62:63]
	v_cmp_eq_u32_e64 s[64:65], 2, v37
	v_cmp_ne_u32_e64 s[66:67], 0, v37
	s_nop 0
	v_cndmask_b32_e64 v38, 0, 1.0, s[64:65]
	v_cmp_gt_u32_e64 s[64:65], 3, v37
	s_nop 1
	v_cndmask_b32_e64 v38, v214, v38, s[64:65]
	v_cmp_lt_i32_e64 s[64:65], 8, v122
	v_fmac_f32_e32 v38, 0x3e38aa3b, v53
	s_and_b64 s[64:65], s[64:65], s[66:67]
	v_cndmask_b32_e64 v37, v212, v38, s[64:65]
	v_cmp_gt_i32_e64 s[64:65], s6, v122
	s_movk_i32 s6, 0x20b
	s_nop 0
	v_cndmask_b32_e64 v38, 0, 1, s[64:65]
	v_cmp_gt_i32_e64 s[64:65], s6, v122
	s_and_b64 s[18:19], s[46:47], s[64:65]
	v_cndmask_b32_e64 v40, 0, 1, s[18:19]
	v_cmp_eq_u32_e64 s[64:65], 10, v39
	s_movk_i32 s6, 0x8c
	s_nop 0
	v_addc_co_u32_e64 v38, s[66:67], v40, v38, s[64:65]
	v_cmp_eq_u32_e64 s[66:67], 2, v38
	v_cmp_ne_u32_e64 s[68:69], 0, v38
	s_nop 0
	v_cndmask_b32_e64 v40, 0, 1.0, s[66:67]
	v_cmp_gt_u32_e64 s[66:67], 3, v38
	s_nop 1
	v_cndmask_b32_e64 v40, v214, v40, s[66:67]
	v_cmp_lt_i32_e64 s[66:67], 9, v122
	v_fmac_f32_e32 v40, 0x3e38aa3b, v54
	s_and_b64 s[66:67], s[66:67], s[68:69]
	v_cndmask_b32_e64 v38, v212, v40, s[66:67]
	v_cmp_gt_i32_e64 s[66:67], s6, v122
	s_movk_i32 s6, 0x20c
	s_nop 0
	v_cndmask_b32_e64 v40, 0, 1, s[66:67]
	v_cmp_gt_i32_e64 s[66:67], s6, v122
	s_and_b64 s[18:19], s[48:49], s[66:67]
	v_cndmask_b32_e64 v41, 0, 1, s[18:19]
	v_cmp_eq_u32_e64 s[66:67], 11, v39
	s_movk_i32 s6, 0x91
	s_nop 0
	v_addc_co_u32_e64 v39, s[68:69], v41, v40, s[66:67]
	v_cmp_eq_u32_e64 s[68:69], 2, v39
	v_cmp_ne_u32_e64 s[70:71], 0, v39
	s_nop 0
	v_cndmask_b32_e64 v40, 0, 1.0, s[68:69]
	v_cmp_gt_u32_e64 s[68:69], 3, v39
	s_nop 1
	v_cndmask_b32_e64 v40, v214, v40, s[68:69]
	v_cmp_lt_i32_e64 s[68:69], 10, v122
	v_fmac_f32_e32 v40, 0x3e38aa3b, v55
	s_and_b64 s[68:69], s[68:69], s[70:71]
	v_cndmask_b32_e64 v39, v212, v40, s[68:69]
	v_cmp_gt_i32_e64 s[68:69], s6, v122
	s_movk_i32 s6, 0x211
	s_nop 0
	v_cndmask_b32_e64 v40, 0, 1, s[68:69]
	v_cmp_gt_i32_e64 s[68:69], s6, v122
	s_and_b64 s[18:19], s[42:43], s[68:69]
	v_cndmask_b32_e64 v41, 0, 1, s[18:19]
	v_addc_co_u32_e32 v40, vcc, v41, v40, vcc
	v_cmp_eq_u32_e32 vcc, 2, v40
	v_cmp_ne_u32_e64 s[68:69], 0, v40
	s_movk_i32 s6, 0x92
	v_cndmask_b32_e64 v41, 0, 1.0, vcc
	v_cmp_gt_u32_e32 vcc, 3, v40
	s_nop 1
	v_cndmask_b32_e32 v41, v214, v41, vcc
	v_cmp_lt_i32_e32 vcc, 15, v122
	v_fmac_f32_e32 v41, 0x3e38aa3b, v56
	s_and_b64 vcc, vcc, s[68:69]
	v_cndmask_b32_e32 v40, v212, v41, vcc
	v_cmp_gt_i32_e32 vcc, s6, v122
	s_movk_i32 s6, 0x212
	s_nop 0
	v_cndmask_b32_e64 v41, 0, 1, vcc
	v_cmp_gt_i32_e32 vcc, s6, v122
	s_and_b64 s[18:19], s[44:45], vcc
	v_cndmask_b32_e64 v42, 0, 1, s[18:19]
	v_addc_co_u32_e64 v41, vcc, v42, v41, s[54:55]
	v_cmp_eq_u32_e32 vcc, 2, v41
	v_cmp_ne_u32_e64 s[54:55], 0, v41
	s_movk_i32 s6, 0x93
	v_cndmask_b32_e64 v42, 0, 1.0, vcc
	v_cmp_gt_u32_e32 vcc, 3, v41
	s_nop 1
	v_cndmask_b32_e32 v42, v214, v42, vcc
	v_cmp_lt_i32_e32 vcc, 16, v122
	v_fmac_f32_e32 v42, 0x3e38aa3b, v57
	s_and_b64 vcc, vcc, s[54:55]
	v_cndmask_b32_e32 v41, v212, v42, vcc
	v_cmp_gt_i32_e32 vcc, s6, v122
	s_movk_i32 s6, 0x213
	s_nop 0
	v_cndmask_b32_e64 v42, 0, 1, vcc
	v_cmp_gt_i32_e32 vcc, s6, v122
	s_and_b64 s[18:19], s[46:47], vcc
	v_cndmask_b32_e64 v43, 0, 1, s[18:19]
	v_addc_co_u32_e64 v42, vcc, v43, v42, s[56:57]
	v_cmp_eq_u32_e32 vcc, 2, v42
	v_cmp_ne_u32_e64 s[54:55], 0, v42
	s_movk_i32 s6, 0x94
	v_cndmask_b32_e64 v43, 0, 1.0, vcc
	v_cmp_gt_u32_e32 vcc, 3, v42
	s_nop 1
	v_cndmask_b32_e32 v43, v214, v43, vcc
	v_cmp_lt_i32_e32 vcc, 17, v122
	v_fmac_f32_e32 v43, 0x3e38aa3b, v58
	s_and_b64 vcc, vcc, s[54:55]
	v_cndmask_b32_e32 v42, v212, v43, vcc
	v_cmp_gt_i32_e32 vcc, s6, v122
	s_movk_i32 s6, 0x214
	s_nop 0
	v_cndmask_b32_e64 v43, 0, 1, vcc
	v_cmp_gt_i32_e32 vcc, s6, v122
	s_and_b64 s[18:19], s[48:49], vcc
	v_cndmask_b32_e64 v44, 0, 1, s[18:19]
	v_addc_co_u32_e64 v43, vcc, v44, v43, s[58:59]
	v_cmp_eq_u32_e32 vcc, 2, v43
	v_cmp_ne_u32_e64 s[54:55], 0, v43
	s_movk_i32 s6, 0x99
	v_cndmask_b32_e64 v44, 0, 1.0, vcc
	v_cmp_gt_u32_e32 vcc, 3, v43
	s_nop 1
	v_cndmask_b32_e32 v44, v214, v44, vcc
	v_cmp_lt_i32_e32 vcc, 18, v122
	v_fmac_f32_e32 v44, 0x3e38aa3b, v59
	s_and_b64 vcc, vcc, s[54:55]
	v_cndmask_b32_e32 v43, v212, v44, vcc
	v_cmp_gt_i32_e32 vcc, s6, v122
	s_movk_i32 s6, 0x219
	s_nop 0
	v_cndmask_b32_e64 v44, 0, 1, vcc
	v_cmp_gt_i32_e32 vcc, s6, v122
	s_and_b64 s[18:19], s[42:43], vcc
	v_cndmask_b32_e64 v45, 0, 1, s[18:19]
	v_addc_co_u32_e64 v44, vcc, v45, v44, s[60:61]
	v_cmp_eq_u32_e32 vcc, 2, v44
	v_cmp_ne_u32_e64 s[54:55], 0, v44
	s_movk_i32 s6, 0x9a
	v_cndmask_b32_e64 v45, 0, 1.0, vcc
	v_cmp_gt_u32_e32 vcc, 3, v44
	s_nop 1
	v_cndmask_b32_e32 v45, v214, v45, vcc
	v_cmp_lt_i32_e32 vcc, 23, v122
	v_fmac_f32_e32 v45, 0x3e38aa3b, v60
	s_and_b64 vcc, vcc, s[54:55]
	v_cndmask_b32_e32 v44, v212, v45, vcc
	v_cmp_gt_i32_e32 vcc, s6, v122
	s_movk_i32 s6, 0x21a
	s_nop 0
	v_cndmask_b32_e64 v45, 0, 1, vcc
	v_cmp_gt_i32_e32 vcc, s6, v122
	s_and_b64 s[18:19], s[44:45], vcc
	v_cndmask_b32_e64 v46, 0, 1, s[18:19]
	v_addc_co_u32_e64 v45, vcc, v46, v45, s[62:63]
	v_cmp_eq_u32_e32 vcc, 2, v45
	v_cmp_ne_u32_e64 s[54:55], 0, v45
	s_movk_i32 s6, 0x9b
	v_cndmask_b32_e64 v46, 0, 1.0, vcc
	v_cmp_gt_u32_e32 vcc, 3, v45
	s_nop 1
	v_cndmask_b32_e32 v46, v214, v46, vcc
	v_cmp_lt_i32_e32 vcc, 24, v122
	v_fmac_f32_e32 v46, 0x3e38aa3b, v61
	s_and_b64 vcc, vcc, s[54:55]
	v_cndmask_b32_e32 v45, v212, v46, vcc
	v_cmp_gt_i32_e32 vcc, s6, v122
	s_movk_i32 s6, 0x21b
	s_nop 0
	v_cndmask_b32_e64 v46, 0, 1, vcc
	v_cmp_gt_i32_e32 vcc, s6, v122
	s_and_b64 s[18:19], s[46:47], vcc
	v_cndmask_b32_e64 v47, 0, 1, s[18:19]
	v_addc_co_u32_e64 v46, vcc, v47, v46, s[64:65]
	v_cmp_eq_u32_e32 vcc, 2, v46
	v_cmp_ne_u32_e64 s[54:55], 0, v46
	s_movk_i32 s6, 0x9c
	v_cndmask_b32_e64 v47, 0, 1.0, vcc
	v_cmp_gt_u32_e32 vcc, 3, v46
	s_nop 1
	v_cndmask_b32_e32 v47, v214, v47, vcc
	v_cmp_lt_i32_e32 vcc, 25, v122
	v_fmac_f32_e32 v47, 0x3e38aa3b, v62
	s_and_b64 vcc, vcc, s[54:55]
	v_cndmask_b32_e32 v46, v212, v47, vcc
	v_cmp_gt_i32_e32 vcc, s6, v122
	s_movk_i32 s6, 0x21c
	s_nop 0
	v_cndmask_b32_e64 v47, 0, 1, vcc
	v_cmp_gt_i32_e32 vcc, s6, v122
	s_and_b64 s[18:19], s[48:49], vcc
	v_cndmask_b32_e64 v123, 0, 1, s[18:19]
	v_addc_co_u32_e64 v47, vcc, v123, v47, s[66:67]
	v_cmp_eq_u32_e32 vcc, 2, v47
	v_cmp_ne_u32_e64 s[54:55], 0, v47
	s_mov_b64 s[18:19], 0
	v_cndmask_b32_e64 v123, 0, 1.0, vcc
	v_cmp_gt_u32_e32 vcc, 3, v47
	s_nop 1
	v_cndmask_b32_e32 v123, v214, v123, vcc
	v_cmp_lt_i32_e32 vcc, 26, v122
	v_fmac_f32_e32 v123, 0x3e38aa3b, v63
	s_and_b64 vcc, vcc, s[54:55]
	v_cndmask_b32_e32 v47, v212, v123, vcc

.LBB0_765:
	v_add_u32_e32 v196, v99, v111
	v_add_u32_e32 v197, 0x2000, v196
	ds_read2_b64 v[180:183], v197 offset0:128 offset1:130
	ds_read2_b64 v[184:187], v197 offset0:132 offset1:134
	v_add_u32_e32 v197, 0x3000, v196
	ds_read2_b64 v[188:191], v197 offset0:160 offset1:162
	ds_read2_b64 v[192:195], v197 offset0:164 offset1:166
	v_sub_f32_e32 v32, v32, v49
	v_exp_f32_e32 v32, v32
	v_sub_f32_e32 v33, v33, v49
	v_exp_f32_e32 v33, v33
	v_sub_f32_e32 v34, v34, v49
	v_exp_f32_e32 v34, v34
	v_sub_f32_e32 v35, v35, v49
	v_exp_f32_e32 v35, v35
	v_sub_f32_e32 v36, v36, v49
	v_add_f32_e32 v50, 0, v32
	v_exp_f32_e32 v36, v36
	v_sub_f32_e32 v37, v37, v49
	v_add_f32_e32 v50, v33, v50
	v_exp_f32_e32 v37, v37
	v_sub_f32_e32 v38, v38, v49
	v_add_f32_e32 v50, v34, v50
	v_exp_f32_e32 v38, v38
	v_sub_f32_e32 v39, v39, v49
	v_add_f32_e32 v50, v35, v50
	v_exp_f32_e32 v39, v39
	v_sub_f32_e32 v40, v40, v49
	v_add_f32_e32 v50, v36, v50
	v_exp_f32_e32 v40, v40
	v_sub_f32_e32 v41, v41, v49
	v_add_f32_e32 v50, v37, v50
	v_exp_f32_e32 v41, v41
	v_sub_f32_e32 v42, v42, v49
	v_add_f32_e32 v50, v38, v50
	v_exp_f32_e32 v42, v42
	v_sub_f32_e32 v43, v43, v49
	v_add_f32_e32 v50, v39, v50
	v_exp_f32_e32 v43, v43
	v_sub_f32_e32 v44, v44, v49
	v_add_f32_e32 v50, v40, v50
	v_exp_f32_e32 v44, v44
	v_sub_f32_e32 v45, v45, v49
	v_add_f32_e32 v50, v41, v50
	v_exp_f32_e32 v45, v45
	v_sub_f32_e32 v46, v46, v49
	v_add_f32_e32 v50, v42, v50
	v_exp_f32_e32 v46, v46
	v_sub_f32_e32 v47, v47, v49
	v_add_f32_e32 v50, v43, v50
	v_exp_f32_e32 v47, v47
	v_add_f32_e32 v50, v44, v50
	v_add_f32_e32 v50, v45, v50
	v_add_f32_e32 v50, v46, v50
	v_add_f32_e32 v49, v47, v50
	v_fmac_f32_e32 v49, v103, v48
	v_add_u32_e32 v48, v99, v111
	v_cvt_pk_bf16_f32 v32, v32, v33
	v_cvt_pk_bf16_f32 v33, v34, v35
	v_cvt_pk_bf16_f32 v35, v38, v39
	v_cvt_pk_bf16_f32 v38, v44, v45
	v_add_u32_e32 v44, 0x2000, v48
	v_cvt_pk_bf16_f32 v34, v36, v37
	v_cvt_pk_bf16_f32 v36, v40, v41
	v_cvt_pk_bf16_f32 v37, v42, v43
	v_cvt_pk_bf16_f32 v39, v46, v47
	s_waitcnt lgkmcnt(0)
	v_mfma_f32_32x32x16_bf16 v[16:31], v[180:183], v[32:35], v[16:31]
	v_mfma_f32_32x32x16_bf16 v[16:31], v[184:187], v[36:39], v[16:31]
	s_waitcnt lgkmcnt(0)
	v_mfma_f32_32x32x16_bf16 v[0:15], v[188:191], v[32:35], v[0:15]
	v_mfma_f32_32x32x16_bf16 v[0:15], v[192:195], v[36:39], v[0:15]
	v_mov_b32_e32 v103, v49
	s_cmp_gt_i32 s92, s86
	s_cbranch_scc1 .LBB0_746
	s_branch .LBB0_767

.LBB0_767:
	ds_read_b128 v[32:35], v121 offset:4608
	ds_read_b128 v[36:39], v121 offset:4640
	ds_read_b128 v[40:43], v121 offset:4672
	ds_read_b128 v[44:47], v121 offset:4704
	s_waitcnt lgkmcnt(0)
	v_mfma_f32_32x32x16_bf16 v[48:63], v[32:35], v[64:67], 0
	v_mfma_f32_32x32x16_bf16 v[48:63], v[36:39], v[68:71], v[48:63]
	v_mfma_f32_32x32x16_bf16 v[48:63], v[40:43], v[72:75], v[48:63]
	v_mfma_f32_32x32x16_bf16 v[48:63], v[44:47], v[76:79], v[48:63]
	s_add_i32 s6, s89, 0xffffffa2
	v_subrev_u32_e32 v120, 63, v105
	s_cmpk_gt_i32 s6, 0x200
	s_mov_b64 s[18:19], -1
	s_cbranch_scc1 .LBB0_777
	s_sub_i32 s33, s89, 32
	s_cmpk_gt_i32 s6, 0x80
	s_cselect_b64 s[18:19], -1, 0
	s_cmpk_lt_i32 s33, 0x201
	s_cselect_b64 s[54:55], -1, 0
	s_and_b64 s[54:55], s[18:19], s[54:55]
	s_mov_b64 s[18:19], -1
	s_and_b64 vcc, exec, s[54:55]
	s_cbranch_vccnz .LBB0_774
	s_cmp_gt_i32 s6, -1
	s_cselect_b64 s[18:19], -1, 0
	s_cmpk_lt_i32 s33, 0x81
	s_cselect_b64 s[54:55], -1, 0
	s_and_b64 s[54:55], s[18:19], s[54:55]
	s_mov_b64 s[18:19], -1
	s_and_b64 vcc, exec, s[54:55]
	s_cbranch_vccnz .LBB0_771
	s_movk_i32 s6, 0x81
	v_cmp_gt_i32_e32 vcc, s6, v120
	s_movk_i32 s6, 0x201
	v_and_b32_e32 v39, 15, v120
	v_cndmask_b32_e64 v32, 0, 1, vcc
	v_cmp_gt_i32_e32 vcc, s6, v120
	s_and_b64 s[18:19], s[42:43], vcc
	v_cndmask_b32_e64 v33, 0, 1, s[18:19]
	v_cmp_eq_u32_e32 vcc, 0, v39
	s_movk_i32 s6, 0x82
	s_nop 0
	v_addc_co_u32_e64 v32, s[54:55], v33, v32, vcc
	v_cmp_eq_u32_e64 s[54:55], 2, v32
	v_cmp_ne_u32_e64 s[56:57], 0, v32
	s_nop 0
	v_cndmask_b32_e64 v33, 0, 1.0, s[54:55]
	v_cmp_gt_u32_e64 s[54:55], 3, v32
	s_nop 1
	v_cndmask_b32_e64 v33, v214, v33, s[54:55]
	v_cmp_lt_i32_e64 s[54:55], -1, v120
	v_fmac_f32_e32 v33, 0x3e38aa3b, v48
	s_and_b64 s[54:55], s[54:55], s[56:57]
	v_cndmask_b32_e64 v32, v212, v33, s[54:55]
	v_cmp_gt_i32_e64 s[54:55], s6, v120
	s_movk_i32 s6, 0x202
	s_nop 0
	v_cndmask_b32_e64 v33, 0, 1, s[54:55]
	v_cmp_gt_i32_e64 s[54:55], s6, v120
	s_and_b64 s[18:19], s[44:45], s[54:55]
	v_cndmask_b32_e64 v34, 0, 1, s[18:19]
	v_cmp_eq_u32_e64 s[54:55], 1, v39
	s_movk_i32 s6, 0x83
	s_nop 0
	v_addc_co_u32_e64 v33, s[56:57], v34, v33, s[54:55]
	v_cmp_eq_u32_e64 s[56:57], 2, v33
	v_cmp_ne_u32_e64 s[58:59], 0, v33
	s_nop 0
	v_cndmask_b32_e64 v34, 0, 1.0, s[56:57]
	v_cmp_gt_u32_e64 s[56:57], 3, v33
	s_nop 1
	v_cndmask_b32_e64 v34, v214, v34, s[56:57]
	v_cmp_lt_i32_e64 s[56:57], 0, v120
	v_fmac_f32_e32 v34, 0x3e38aa3b, v49
	s_and_b64 s[56:57], s[56:57], s[58:59]
	v_cndmask_b32_e64 v33, v212, v34, s[56:57]
	v_cmp_gt_i32_e64 s[56:57], s6, v120
	s_movk_i32 s6, 0x203
	s_nop 0
	v_cndmask_b32_e64 v34, 0, 1, s[56:57]
	v_cmp_gt_i32_e64 s[56:57], s6, v120
	s_and_b64 s[18:19], s[46:47], s[56:57]
	v_cndmask_b32_e64 v35, 0, 1, s[18:19]
	v_cmp_eq_u32_e64 s[56:57], 2, v39
	s_movk_i32 s6, 0x84
	s_nop 0
	v_addc_co_u32_e64 v34, s[58:59], v35, v34, s[56:57]
	v_cmp_eq_u32_e64 s[58:59], 2, v34
	v_cmp_ne_u32_e64 s[60:61], 0, v34
	s_nop 0
	v_cndmask_b32_e64 v35, 0, 1.0, s[58:59]
	v_cmp_gt_u32_e64 s[58:59], 3, v34
	s_nop 1
	v_cndmask_b32_e64 v35, v214, v35, s[58:59]
	v_cmp_lt_i32_e64 s[58:59], 1, v120
	v_fmac_f32_e32 v35, 0x3e38aa3b, v50
	s_and_b64 s[58:59], s[58:59], s[60:61]
	v_cndmask_b32_e64 v34, v212, v35, s[58:59]
	v_cmp_gt_i32_e64 s[58:59], s6, v120
	s_movk_i32 s6, 0x204
	s_nop 0
	v_cndmask_b32_e64 v35, 0, 1, s[58:59]
	v_cmp_gt_i32_e64 s[58:59], s6, v120
	s_and_b64 s[18:19], s[48:49], s[58:59]
	v_cndmask_b32_e64 v36, 0, 1, s[18:19]
	v_cmp_eq_u32_e64 s[58:59], 3, v39
	s_movk_i32 s6, 0x89
	s_nop 0
	v_addc_co_u32_e64 v35, s[60:61], v36, v35, s[58:59]
	v_cmp_eq_u32_e64 s[60:61], 2, v35
	v_cmp_ne_u32_e64 s[62:63], 0, v35
	s_nop 0
	v_cndmask_b32_e64 v36, 0, 1.0, s[60:61]
	v_cmp_gt_u32_e64 s[60:61], 3, v35
	s_nop 1
	v_cndmask_b32_e64 v36, v214, v36, s[60:61]
	v_cmp_lt_i32_e64 s[60:61], 2, v120
	v_fmac_f32_e32 v36, 0x3e38aa3b, v51
	s_and_b64 s[60:61], s[60:61], s[62:63]
	v_cndmask_b32_e64 v35, v212, v36, s[60:61]
	v_cmp_gt_i32_e64 s[60:61], s6, v120
	s_movk_i32 s6, 0x209
	s_nop 0
	v_cndmask_b32_e64 v36, 0, 1, s[60:61]
	v_cmp_gt_i32_e64 s[60:61], s6, v120
	s_and_b64 s[18:19], s[42:43], s[60:61]
	v_cndmask_b32_e64 v37, 0, 1, s[18:19]
	v_cmp_eq_u32_e64 s[60:61], 8, v39
	s_movk_i32 s6, 0x8a
	s_nop 0
	v_addc_co_u32_e64 v36, s[62:63], v37, v36, s[60:61]
	v_cmp_eq_u32_e64 s[62:63], 2, v36
	v_cmp_ne_u32_e64 s[64:65], 0, v36
	s_nop 0
	v_cndmask_b32_e64 v37, 0, 1.0, s[62:63]
	v_cmp_gt_u32_e64 s[62:63], 3, v36
	s_nop 1
	v_cndmask_b32_e64 v37, v214, v37, s[62:63]
	v_cmp_lt_i32_e64 s[62:63], 7, v120
	v_fmac_f32_e32 v37, 0x3e38aa3b, v52
	s_and_b64 s[62:63], s[62:63], s[64:65]
	v_cndmask_b32_e64 v36, v212, v37, s[62:63]
	v_cmp_gt_i32_e64 s[62:63], s6, v120
	s_movk_i32 s6, 0x20a
	s_nop 0
	v_cndmask_b32_e64 v37, 0, 1, s[62:63]
	v_cmp_gt_i32_e64 s[62:63], s6, v120
	s_and_b64 s[18:19], s[44:45], s[62:63]
	v_cndmask_b32_e64 v38, 0, 1, s[18:19]
	v_cmp_eq_u32_e64 s[62:63], 9, v39
	s_movk_i32 s6, 0x8b
	s_nop 0
	v_addc_co_u32_e64 v37, s[64:65], v38, v37, s[62:63]
	v_cmp_eq_u32_e64 s[64:65], 2, v37
	v_cmp_ne_u32_e64 s[66:67], 0, v37
	s_nop 0
	v_cndmask_b32_e64 v38, 0, 1.0, s[64:65]
	v_cmp_gt_u32_e64 s[64:65], 3, v37
	s_nop 1
	v_cndmask_b32_e64 v38, v214, v38, s[64:65]
	v_cmp_lt_i32_e64 s[64:65], 8, v120
	v_fmac_f32_e32 v38, 0x3e38aa3b, v53
	s_and_b64 s[64:65], s[64:65], s[66:67]
	v_cndmask_b32_e64 v37, v212, v38, s[64:65]
	v_cmp_gt_i32_e64 s[64:65], s6, v120
	s_movk_i32 s6, 0x20b
	s_nop 0
	v_cndmask_b32_e64 v38, 0, 1, s[64:65]
	v_cmp_gt_i32_e64 s[64:65], s6, v120
	s_and_b64 s[18:19], s[46:47], s[64:65]
	v_cndmask_b32_e64 v40, 0, 1, s[18:19]
	v_cmp_eq_u32_e64 s[64:65], 10, v39
	s_movk_i32 s6, 0x8c
	s_nop 0
	v_addc_co_u32_e64 v38, s[66:67], v40, v38, s[64:65]
	v_cmp_eq_u32_e64 s[66:67], 2, v38
	v_cmp_ne_u32_e64 s[68:69], 0, v38
	s_nop 0
	v_cndmask_b32_e64 v40, 0, 1.0, s[66:67]
	v_cmp_gt_u32_e64 s[66:67], 3, v38
	s_nop 1
	v_cndmask_b32_e64 v40, v214, v40, s[66:67]
	v_cmp_lt_i32_e64 s[66:67], 9, v120
	v_fmac_f32_e32 v40, 0x3e38aa3b, v54
	s_and_b64 s[66:67], s[66:67], s[68:69]
	v_cndmask_b32_e64 v38, v212, v40, s[66:67]
	v_cmp_gt_i32_e64 s[66:67], s6, v120
	s_movk_i32 s6, 0x20c
	s_nop 0
	v_cndmask_b32_e64 v40, 0, 1, s[66:67]
	v_cmp_gt_i32_e64 s[66:67], s6, v120
	s_and_b64 s[18:19], s[48:49], s[66:67]
	v_cndmask_b32_e64 v41, 0, 1, s[18:19]
	v_cmp_eq_u32_e64 s[66:67], 11, v39
	s_movk_i32 s6, 0x91
	s_nop 0
	v_addc_co_u32_e64 v39, s[68:69], v41, v40, s[66:67]
	v_cmp_eq_u32_e64 s[68:69], 2, v39
	v_cmp_ne_u32_e64 s[70:71], 0, v39
	s_nop 0
	v_cndmask_b32_e64 v40, 0, 1.0, s[68:69]
	v_cmp_gt_u32_e64 s[68:69], 3, v39
	s_nop 1
	v_cndmask_b32_e64 v40, v214, v40, s[68:69]
	v_cmp_lt_i32_e64 s[68:69], 10, v120
	v_fmac_f32_e32 v40, 0x3e38aa3b, v55
	s_and_b64 s[68:69], s[68:69], s[70:71]
	v_cndmask_b32_e64 v39, v212, v40, s[68:69]
	v_cmp_gt_i32_e64 s[68:69], s6, v120
	s_movk_i32 s6, 0x211
	s_nop 0
	v_cndmask_b32_e64 v40, 0, 1, s[68:69]
	v_cmp_gt_i32_e64 s[68:69], s6, v120
	s_and_b64 s[18:19], s[42:43], s[68:69]
	v_cndmask_b32_e64 v41, 0, 1, s[18:19]
	v_addc_co_u32_e32 v40, vcc, v41, v40, vcc
	v_cmp_eq_u32_e32 vcc, 2, v40
	v_cmp_ne_u32_e64 s[68:69], 0, v40
	s_movk_i32 s6, 0x92
	v_cndmask_b32_e64 v41, 0, 1.0, vcc
	v_cmp_gt_u32_e32 vcc, 3, v40
	s_nop 1
	v_cndmask_b32_e32 v41, v214, v41, vcc
	v_cmp_lt_i32_e32 vcc, 15, v120
	v_fmac_f32_e32 v41, 0x3e38aa3b, v56
	s_and_b64 vcc, vcc, s[68:69]
	v_cndmask_b32_e32 v40, v212, v41, vcc
	v_cmp_gt_i32_e32 vcc, s6, v120
	s_movk_i32 s6, 0x212
	s_nop 0
	v_cndmask_b32_e64 v41, 0, 1, vcc
	v_cmp_gt_i32_e32 vcc, s6, v120
	s_and_b64 s[18:19], s[44:45], vcc
	v_cndmask_b32_e64 v42, 0, 1, s[18:19]
	v_addc_co_u32_e64 v41, vcc, v42, v41, s[54:55]
	v_cmp_eq_u32_e32 vcc, 2, v41
	v_cmp_ne_u32_e64 s[54:55], 0, v41
	s_movk_i32 s6, 0x93
	v_cndmask_b32_e64 v42, 0, 1.0, vcc
	v_cmp_gt_u32_e32 vcc, 3, v41
	s_nop 1
	v_cndmask_b32_e32 v42, v214, v42, vcc
	v_cmp_lt_i32_e32 vcc, 16, v120
	v_fmac_f32_e32 v42, 0x3e38aa3b, v57
	s_and_b64 vcc, vcc, s[54:55]
	v_cndmask_b32_e32 v41, v212, v42, vcc
	v_cmp_gt_i32_e32 vcc, s6, v120
	s_movk_i32 s6, 0x213
	s_nop 0
	v_cndmask_b32_e64 v42, 0, 1, vcc
	v_cmp_gt_i32_e32 vcc, s6, v120
	s_and_b64 s[18:19], s[46:47], vcc
	v_cndmask_b32_e64 v43, 0, 1, s[18:19]
	v_addc_co_u32_e64 v42, vcc, v43, v42, s[56:57]
	v_cmp_eq_u32_e32 vcc, 2, v42
	v_cmp_ne_u32_e64 s[54:55], 0, v42
	s_movk_i32 s6, 0x94
	v_cndmask_b32_e64 v43, 0, 1.0, vcc
	v_cmp_gt_u32_e32 vcc, 3, v42
	s_nop 1
	v_cndmask_b32_e32 v43, v214, v43, vcc
	v_cmp_lt_i32_e32 vcc, 17, v120
	v_fmac_f32_e32 v43, 0x3e38aa3b, v58
	s_and_b64 vcc, vcc, s[54:55]
	v_cndmask_b32_e32 v42, v212, v43, vcc
	v_cmp_gt_i32_e32 vcc, s6, v120
	s_movk_i32 s6, 0x214
	s_nop 0
	v_cndmask_b32_e64 v43, 0, 1, vcc
	v_cmp_gt_i32_e32 vcc, s6, v120
	s_and_b64 s[18:19], s[48:49], vcc
	v_cndmask_b32_e64 v44, 0, 1, s[18:19]
	v_addc_co_u32_e64 v43, vcc, v44, v43, s[58:59]
	v_cmp_eq_u32_e32 vcc, 2, v43
	v_cmp_ne_u32_e64 s[54:55], 0, v43
	s_movk_i32 s6, 0x99
	v_cndmask_b32_e64 v44, 0, 1.0, vcc
	v_cmp_gt_u32_e32 vcc, 3, v43
	s_nop 1
	v_cndmask_b32_e32 v44, v214, v44, vcc
	v_cmp_lt_i32_e32 vcc, 18, v120
	v_fmac_f32_e32 v44, 0x3e38aa3b, v59
	s_and_b64 vcc, vcc, s[54:55]
	v_cndmask_b32_e32 v43, v212, v44, vcc
	v_cmp_gt_i32_e32 vcc, s6, v120
	s_movk_i32 s6, 0x219
	s_nop 0
	v_cndmask_b32_e64 v44, 0, 1, vcc
	v_cmp_gt_i32_e32 vcc, s6, v120
	s_and_b64 s[18:19], s[42:43], vcc
	v_cndmask_b32_e64 v45, 0, 1, s[18:19]
	v_addc_co_u32_e64 v44, vcc, v45, v44, s[60:61]
	v_cmp_eq_u32_e32 vcc, 2, v44
	v_cmp_ne_u32_e64 s[54:55], 0, v44
	s_movk_i32 s6, 0x9a
	v_cndmask_b32_e64 v45, 0, 1.0, vcc
	v_cmp_gt_u32_e32 vcc, 3, v44
	s_nop 1
	v_cndmask_b32_e32 v45, v214, v45, vcc
	v_cmp_lt_i32_e32 vcc, 23, v120
	v_fmac_f32_e32 v45, 0x3e38aa3b, v60
	s_and_b64 vcc, vcc, s[54:55]
	v_cndmask_b32_e32 v44, v212, v45, vcc
	v_cmp_gt_i32_e32 vcc, s6, v120
	s_movk_i32 s6, 0x21a
	s_nop 0
	v_cndmask_b32_e64 v45, 0, 1, vcc
	v_cmp_gt_i32_e32 vcc, s6, v120
	s_and_b64 s[18:19], s[44:45], vcc
	v_cndmask_b32_e64 v46, 0, 1, s[18:19]
	v_addc_co_u32_e64 v45, vcc, v46, v45, s[62:63]
	v_cmp_eq_u32_e32 vcc, 2, v45
	v_cmp_ne_u32_e64 s[54:55], 0, v45
	s_movk_i32 s6, 0x9b
	v_cndmask_b32_e64 v46, 0, 1.0, vcc
	v_cmp_gt_u32_e32 vcc, 3, v45
	s_nop 1
	v_cndmask_b32_e32 v46, v214, v46, vcc
	v_cmp_lt_i32_e32 vcc, 24, v120
	v_fmac_f32_e32 v46, 0x3e38aa3b, v61
	s_and_b64 vcc, vcc, s[54:55]
	v_cndmask_b32_e32 v45, v212, v46, vcc
	v_cmp_gt_i32_e32 vcc, s6, v120
	s_movk_i32 s6, 0x21b
	s_nop 0
	v_cndmask_b32_e64 v46, 0, 1, vcc
	v_cmp_gt_i32_e32 vcc, s6, v120
	s_and_b64 s[18:19], s[46:47], vcc
	v_cndmask_b32_e64 v47, 0, 1, s[18:19]
	v_addc_co_u32_e64 v46, vcc, v47, v46, s[64:65]
	v_cmp_eq_u32_e32 vcc, 2, v46
	v_cmp_ne_u32_e64 s[54:55], 0, v46
	s_movk_i32 s6, 0x9c
	v_cndmask_b32_e64 v47, 0, 1.0, vcc
	v_cmp_gt_u32_e32 vcc, 3, v46
	s_nop 1
	v_cndmask_b32_e32 v47, v214, v47, vcc
	v_cmp_lt_i32_e32 vcc, 25, v120
	v_fmac_f32_e32 v47, 0x3e38aa3b, v62
	s_and_b64 vcc, vcc, s[54:55]
	v_cndmask_b32_e32 v46, v212, v47, vcc
	v_cmp_gt_i32_e32 vcc, s6, v120
	s_movk_i32 s6, 0x21c
	s_nop 0
	v_cndmask_b32_e64 v47, 0, 1, vcc
	v_cmp_gt_i32_e32 vcc, s6, v120
	s_and_b64 s[18:19], s[48:49], vcc
	v_cndmask_b32_e64 v121, 0, 1, s[18:19]
	v_addc_co_u32_e64 v47, vcc, v121, v47, s[66:67]
	v_cmp_eq_u32_e32 vcc, 2, v47
	v_cmp_ne_u32_e64 s[54:55], 0, v47
	s_mov_b64 s[18:19], 0
	v_cndmask_b32_e64 v121, 0, 1.0, vcc
	v_cmp_gt_u32_e32 vcc, 3, v47
	s_nop 1
	v_cndmask_b32_e32 v121, v214, v121, vcc
	v_cmp_lt_i32_e32 vcc, 26, v120
	v_fmac_f32_e32 v121, 0x3e38aa3b, v63
	s_and_b64 vcc, vcc, s[54:55]
	v_cndmask_b32_e32 v47, v212, v121, vcc

.LBB0_781:
	v_add_u32_e32 v196, v99, v111
	v_add_u32_e32 v197, 0x2000, v196
	ds_read2_b64 v[180:183], v197 offset0:136 offset1:138
	ds_read2_b64 v[184:187], v197 offset0:140 offset1:142
	v_add_u32_e32 v197, 0x3000, v196
	ds_read2_b64 v[188:191], v197 offset0:168 offset1:170
	ds_read2_b64 v[192:195], v197 offset0:172 offset1:174
	v_sub_f32_e32 v32, v32, v49
	v_exp_f32_e32 v32, v32
	v_sub_f32_e32 v33, v33, v49
	v_exp_f32_e32 v33, v33
	v_sub_f32_e32 v34, v34, v49
	v_exp_f32_e32 v34, v34
	v_sub_f32_e32 v35, v35, v49
	v_exp_f32_e32 v35, v35
	v_sub_f32_e32 v36, v36, v49
	v_add_f32_e32 v50, 0, v32
	v_exp_f32_e32 v36, v36
	v_sub_f32_e32 v37, v37, v49
	v_add_f32_e32 v50, v33, v50
	v_exp_f32_e32 v37, v37
	v_sub_f32_e32 v38, v38, v49
	v_add_f32_e32 v50, v34, v50
	v_exp_f32_e32 v38, v38
	v_sub_f32_e32 v39, v39, v49
	v_add_f32_e32 v50, v35, v50
	v_exp_f32_e32 v39, v39
	v_sub_f32_e32 v40, v40, v49
	v_add_f32_e32 v50, v36, v50
	v_exp_f32_e32 v40, v40
	v_sub_f32_e32 v41, v41, v49
	v_add_f32_e32 v50, v37, v50
	v_exp_f32_e32 v41, v41
	v_sub_f32_e32 v42, v42, v49
	v_add_f32_e32 v50, v38, v50
	v_exp_f32_e32 v42, v42
	v_sub_f32_e32 v43, v43, v49
	v_add_f32_e32 v50, v39, v50
	v_exp_f32_e32 v43, v43
	v_sub_f32_e32 v44, v44, v49
	v_add_f32_e32 v50, v40, v50
	v_exp_f32_e32 v44, v44
	v_sub_f32_e32 v45, v45, v49
	v_add_f32_e32 v50, v41, v50
	v_exp_f32_e32 v45, v45
	v_sub_f32_e32 v46, v46, v49
	v_add_f32_e32 v50, v42, v50
	v_exp_f32_e32 v46, v46
	v_sub_f32_e32 v47, v47, v49
	v_add_f32_e32 v50, v43, v50
	v_exp_f32_e32 v47, v47
	v_add_f32_e32 v50, v44, v50
	v_add_f32_e32 v50, v45, v50
	v_add_f32_e32 v50, v46, v50
	v_add_f32_e32 v49, v47, v50
	v_fmac_f32_e32 v49, v103, v48
	v_add_u32_e32 v48, v99, v111
	v_cvt_pk_bf16_f32 v32, v32, v33
	v_cvt_pk_bf16_f32 v33, v34, v35
	v_cvt_pk_bf16_f32 v35, v38, v39
	v_cvt_pk_bf16_f32 v38, v44, v45
	v_add_u32_e32 v44, 0x2000, v48
	v_cvt_pk_bf16_f32 v34, v36, v37
	v_cvt_pk_bf16_f32 v36, v40, v41
	v_cvt_pk_bf16_f32 v37, v42, v43
	v_cvt_pk_bf16_f32 v39, v46, v47
	s_waitcnt lgkmcnt(0)
	v_mfma_f32_32x32x16_bf16 v[16:31], v[180:183], v[32:35], v[16:31]
	v_mfma_f32_32x32x16_bf16 v[16:31], v[184:187], v[36:39], v[16:31]
	s_waitcnt lgkmcnt(0)
	v_mfma_f32_32x32x16_bf16 v[0:15], v[188:191], v[32:35], v[0:15]
	v_mfma_f32_32x32x16_bf16 v[0:15], v[192:195], v[36:39], v[0:15]
	v_mov_b32_e32 v103, v49
	s_branch .LBB0_747

.LBB0_791:
	s_add_i32 s16, s6, 0x60
	s_cmp_le_i32 s16, s18
	s_cselect_b64 s[16:17], -1, 0
	v_add_u32_e32 v32, s33, v97
	v_add_u32_e32 v33, s33, v88
	s_and_b64 s[16:17], s[16:17], s[14:15]
	s_andn2_b64 vcc, exec, s[16:17]
	v_add_u32_e32 v82, v32, v112
	v_add_u32_e32 v81, s6, v96
	v_add_u32_e32 v80, v33, v111
	s_cbranch_vccnz .LBB0_793
	ds_read_b128 v[32:35], v82 offset:4608
	ds_read_b128 v[84:87], v82 offset:4640
	ds_read_b128 v[106:109], v82 offset:4672
	ds_read_b128 v[120:123], v82 offset:4704
	s_waitcnt lgkmcnt(0)
	v_mfma_f32_32x32x16_bf16 v[32:47], v[32:35], v[64:67], 0
	v_mfma_f32_32x32x16_bf16 v[32:47], v[84:87], v[68:71], v[32:47]
	v_mfma_f32_32x32x16_bf16 v[32:47], v[106:109], v[72:75], v[32:47]
	v_mfma_f32_32x32x16_bf16 v[32:47], v[120:123], v[76:79], v[32:47]
	s_nop 10
	v_add_u32_e32 v197, 0x2000, v80
	ds_read2_b64 v[180:183], v197 offset0:136 offset1:138
	ds_read2_b64 v[184:187], v197 offset0:140 offset1:142
	v_add_u32_e32 v197, 0x3000, v80
	ds_read2_b64 v[188:191], v197 offset0:168 offset1:170
	ds_read2_b64 v[192:195], v197 offset0:172 offset1:174
	v_mul_f32_e32 v60, 0x3e000000, v32
	v_mul_f32_e64 v61, |v60|, s37
	v_exp_f32_e32 v61, v61
	v_mul_f32_e32 v84, 0x3e000000, v33
	v_add_u32_e32 v62, 0x60, v81
	v_max_f32_e32 v60, 0, v60
	v_add_f32_e32 v61, 1.0, v61
	s_nop 1
	v_log_f32_e32 v61, v61
	s_nop 0
	v_mul_f32_e32 v85, 0x3f317217, v61
	v_fma_f32 v85, v61, s83, -v85
	v_fmac_f32_e32 v85, 0x3377d1cf, v61
	v_fmac_f32_e32 v85, 0x3f317217, v61
	s_nop 1
	v_mov_b32_e32 v61, v85
	v_mul_f32_e64 v83, |v84|, s37
	v_exp_f32_e32 v83, v83
	v_cmp_lt_i32_e32 vcc, v62, v102
	v_add_f32_e32 v61, v60, v61
	v_fma_f32 v32, v32, s81, -v61
	v_add_f32_e32 v62, 1.0, v83
	v_cndmask_b32_e64 v60, 0, -v61, vcc
	s_nop 0
	v_log_f32_e32 v62, v62
	s_nop 0
	v_cndmask_b32_e32 v83, v212, v32, vcc
	v_max_f32_e32 v32, 0, v84
	v_mul_f32_e32 v61, 0x3f317217, v62
	v_fma_f32 v61, v62, s83, -v61
	v_fmac_f32_e32 v61, 0x3377d1cf, v62
	v_fmac_f32_e32 v61, 0x3f317217, v62
	s_nop 1
	v_mul_f32_e32 v62, 0x3e000000, v34
	v_add_f32_e32 v61, v32, v61
	v_mul_f32_e64 v32, |v62|, s37
	v_exp_f32_e32 v84, v32
	v_add_u32_e32 v32, 0x61, v81
	v_cmp_lt_i32_e32 vcc, v32, v102
	v_fma_f32 v33, v33, s81, -v61
	v_add_f32_e32 v84, 1.0, v84
	v_cndmask_b32_e64 v32, 0, -v61, vcc
	s_nop 0
	v_log_f32_e32 v85, v84
	s_nop 0
	v_cndmask_b32_e32 v84, v212, v33, vcc
	v_max_f32_e32 v33, 0, v62
	v_mul_f32_e32 v61, 0x3f317217, v85
	v_fma_f32 v61, v85, s83, -v61
	v_fmac_f32_e32 v61, 0x3377d1cf, v85
	v_fmac_f32_e32 v61, 0x3f317217, v85
	s_nop 1
	v_add_f32_e32 v33, v33, v61
	v_mul_f32_e32 v61, 0x3e000000, v35
	v_mul_f32_e64 v62, |v61|, s37
	v_exp_f32_e32 v85, v62
	v_add_u32_e32 v62, 0x62, v81
	v_cmp_lt_i32_e32 vcc, v62, v102
	v_add_f32_e32 v85, 1.0, v85
	v_cndmask_b32_e64 v62, 0, -v33, vcc
	v_fma_f32 v33, v34, s81, -v33
	v_log_f32_e32 v85, v85
	s_nop 0
	v_cndmask_b32_e32 v86, v212, v33, vcc
	v_max_f32_e32 v33, 0, v61
	v_mul_f32_e32 v34, 0x3f317217, v85
	v_fma_f32 v34, v85, s83, -v34
	v_fmac_f32_e32 v34, 0x3377d1cf, v85
	v_fmac_f32_e32 v34, 0x3f317217, v85
	s_nop 1
	v_mul_f32_e32 v61, 0x3e000000, v36
	v_add_f32_e32 v33, v33, v34
	v_mul_f32_e64 v34, |v61|, s37
	v_exp_f32_e32 v85, v34
	v_add_u32_e32 v34, 0x63, v81
	v_cmp_lt_i32_e32 vcc, v34, v102
	v_add_f32_e32 v85, 1.0, v85
	v_cndmask_b32_e64 v34, 0, -v33, vcc
	v_fma_f32 v33, v35, s81, -v33
	v_log_f32_e32 v85, v85
	s_nop 0
	v_cndmask_b32_e32 v87, v212, v33, vcc
	v_max_f32_e32 v33, 0, v61
	v_mul_f32_e32 v35, 0x3f317217, v85
	v_fma_f32 v35, v85, s83, -v35
	v_fmac_f32_e32 v35, 0x3377d1cf, v85
	v_fmac_f32_e32 v35, 0x3f317217, v85
	s_nop 1
	v_add_f32_e32 v33, v33, v35
	v_mul_f32_e32 v35, 0x3e000000, v37
	v_mul_f32_e64 v61, |v35|, s37
	v_exp_f32_e32 v61, v61
	v_add_u32_e32 v85, 0x68, v81
	v_cmp_lt_i32_e32 vcc, v85, v102
	v_add_f32_e32 v61, 1.0, v61
	v_cndmask_b32_e64 v85, 0, -v33, vcc
	v_fma_f32 v33, v36, s81, -v33
	v_log_f32_e32 v61, v61
	s_nop 0
	v_cndmask_b32_e32 v99, v212, v33, vcc
	v_max_f32_e32 v33, 0, v35
	v_mul_f32_e32 v35, 0x3f317217, v61
	v_fma_f32 v35, v61, s83, -v35
	v_fmac_f32_e32 v35, 0x3377d1cf, v61
	v_fmac_f32_e32 v35, 0x3f317217, v61
	s_nop 1
	v_add_f32_e32 v33, v33, v35
	v_mul_f32_e32 v35, 0x3e000000, v38
	v_mul_f32_e64 v36, |v35|, s37
	v_exp_f32_e32 v36, v36
	v_add_u32_e32 v61, 0x69, v81
	v_cmp_lt_i32_e32 vcc, v61, v102
	v_add_f32_e32 v36, 1.0, v36
	v_cndmask_b32_e64 v103, 0, -v33, vcc
	v_fma_f32 v33, v37, s81, -v33
	v_log_f32_e32 v36, v36
	s_nop 0
	v_cndmask_b32_e32 v105, v212, v33, vcc
	v_max_f32_e32 v33, 0, v35
	v_add_u32_e32 v37, 0x6a, v81
	v_mul_f32_e32 v35, 0x3f317217, v36
	v_fma_f32 v35, v36, s83, -v35
	v_fmac_f32_e32 v35, 0x3377d1cf, v36
	v_fmac_f32_e32 v35, 0x3f317217, v36
	s_nop 1
	v_add_f32_e32 v33, v33, v35
	v_mul_f32_e32 v35, 0x3e000000, v39
	v_mul_f32_e64 v36, |v35|, s37
	v_exp_f32_e32 v36, v36
	v_cmp_lt_i32_e32 vcc, v37, v102
	v_add_f32_e32 v36, 1.0, v36
	v_cndmask_b32_e64 v106, 0, -v33, vcc
	v_fma_f32 v33, v38, s81, -v33
	v_log_f32_e32 v36, v36
	s_nop 0
	v_cndmask_b32_e32 v107, v212, v33, vcc
	v_max_f32_e32 v33, 0, v35
	v_add_u32_e32 v37, 0x6b, v81
	v_mul_f32_e32 v35, 0x3f317217, v36
	v_fma_f32 v35, v36, s83, -v35
	v_fmac_f32_e32 v35, 0x3377d1cf, v36
	v_fmac_f32_e32 v35, 0x3f317217, v36
	s_nop 1
	v_add_f32_e32 v33, v33, v35
	v_mul_f32_e32 v35, 0x3e000000, v40
	v_mul_f32_e64 v36, |v35|, s37
	v_exp_f32_e32 v36, v36
	v_cmp_lt_i32_e32 vcc, v37, v102
	v_add_f32_e32 v36, 1.0, v36
	v_cndmask_b32_e64 v108, 0, -v33, vcc
	v_fma_f32 v33, v39, s81, -v33
	v_log_f32_e32 v36, v36
	s_nop 0
	v_cndmask_b32_e32 v109, v212, v33, vcc
	v_max_f32_e32 v33, 0, v35
	v_add_u32_e32 v37, 0x70, v81
	v_mul_f32_e32 v35, 0x3f317217, v36
	v_fma_f32 v35, v36, s83, -v35
	v_fmac_f32_e32 v35, 0x3377d1cf, v36
	v_fmac_f32_e32 v35, 0x3f317217, v36
	v_add_u32_e32 v39, 0x71, v81
	s_nop 0
	v_add_f32_e32 v33, v33, v35
	v_mul_f32_e32 v35, 0x3e000000, v41
	v_mul_f32_e64 v36, |v35|, s37
	v_exp_f32_e32 v36, v36
	v_cmp_lt_i32_e32 vcc, v37, v102
	v_add_f32_e32 v36, 1.0, v36
	v_cndmask_b32_e64 v37, 0, -v33, vcc
	v_fma_f32 v33, v40, s81, -v33
	v_log_f32_e32 v36, v36
	s_nop 0
	v_cndmask_b32_e32 v38, v212, v33, vcc
	v_max_f32_e32 v33, 0, v35
	v_mul_f32_e32 v35, 0x3f317217, v36
	v_fma_f32 v35, v36, s83, -v35
	v_fmac_f32_e32 v35, 0x3377d1cf, v36
	v_fmac_f32_e32 v35, 0x3f317217, v36
	s_nop 1
	v_add_f32_e32 v33, v33, v35
	v_mul_f32_e32 v35, 0x3e000000, v42
	v_mul_f32_e64 v36, |v35|, s37
	v_exp_f32_e32 v36, v36
	v_cmp_lt_i32_e32 vcc, v39, v102
	v_add_f32_e32 v36, 1.0, v36
	v_cndmask_b32_e64 v39, 0, -v33, vcc
	v_fma_f32 v33, v41, s81, -v33
	v_log_f32_e32 v36, v36
	s_nop 0
	v_cndmask_b32_e32 v40, v212, v33, vcc
	v_max_f32_e32 v33, 0, v35
	v_add_u32_e32 v41, 0x72, v81
	v_mul_f32_e32 v35, 0x3f317217, v36
	v_fma_f32 v35, v36, s83, -v35
	v_fmac_f32_e32 v35, 0x3377d1cf, v36
	v_fmac_f32_e32 v35, 0x3f317217, v36
	v_add_f32_e32 v37, v37, v39
	s_nop 0
	v_add_f32_e32 v33, v33, v35
	v_mul_f32_e32 v35, 0x3e000000, v43
	v_mul_f32_e64 v36, |v35|, s37
	v_exp_f32_e32 v36, v36
	v_cmp_lt_i32_e32 vcc, v41, v102
	v_add_f32_e32 v36, 1.0, v36
	v_cndmask_b32_e64 v41, 0, -v33, vcc
	v_fma_f32 v33, v42, s81, -v33
	v_log_f32_e32 v36, v36
	s_nop 0
	v_cndmask_b32_e32 v42, v212, v33, vcc
	v_max_f32_e32 v33, 0, v35
	v_add_u32_e32 v61, 0x73, v81
	v_mul_f32_e32 v35, 0x3f317217, v36
	v_fma_f32 v35, v36, s83, -v35
	v_fmac_f32_e32 v35, 0x3377d1cf, v36
	v_fmac_f32_e32 v35, 0x3f317217, v36
	s_nop 1
	v_add_f32_e32 v33, v33, v35
	v_mul_f32_e32 v35, 0x3e000000, v44
	v_mul_f32_e64 v36, |v35|, s37
	v_exp_f32_e32 v36, v36
	v_cmp_lt_i32_e32 vcc, v61, v102
	v_add_f32_e32 v36, 1.0, v36
	v_cndmask_b32_e64 v120, 0, -v33, vcc
	v_fma_f32 v33, v43, s81, -v33
	v_log_f32_e32 v36, v36
	s_nop 0
	v_cndmask_b32_e32 v43, v212, v33, vcc
	v_max_f32_e32 v33, 0, v35
	v_add_u32_e32 v61, 0x78, v81
	v_mul_f32_e32 v35, 0x3f317217, v36
	v_fma_f32 v35, v36, s83, -v35
	v_fmac_f32_e32 v35, 0x3377d1cf, v36
	v_fmac_f32_e32 v35, 0x3f317217, v36
	s_nop 1
	v_add_f32_e32 v33, v33, v35
	v_mul_f32_e32 v35, 0x3e000000, v45
	v_mul_f32_e64 v36, |v35|, s37
	v_exp_f32_e32 v36, v36
	v_cmp_lt_i32_e32 vcc, v61, v102
	v_add_f32_e32 v36, 1.0, v36
	v_cndmask_b32_e64 v121, 0, -v33, vcc
	v_fma_f32 v33, v44, s81, -v33
	v_log_f32_e32 v36, v36
	s_nop 0
	v_cndmask_b32_e32 v44, v212, v33, vcc
	v_max_f32_e32 v33, 0, v35
	v_add_u32_e32 v61, 0x79, v81
	v_mul_f32_e32 v35, 0x3f317217, v36
	v_fma_f32 v35, v36, s83, -v35
	v_fmac_f32_e32 v35, 0x3377d1cf, v36
	v_fmac_f32_e32 v35, 0x3f317217, v36
	s_nop 1
	v_add_f32_e32 v33, v33, v35
	v_mul_f32_e32 v35, 0x3e000000, v46
	v_mul_f32_e64 v36, |v35|, s37
	v_exp_f32_e32 v36, v36
	v_cmp_lt_i32_e32 vcc, v61, v102
	v_add_f32_e32 v36, 1.0, v36
	v_cndmask_b32_e64 v122, 0, -v33, vcc
	v_fma_f32 v33, v45, s81, -v33
	v_log_f32_e32 v36, v36
	s_nop 0
	v_cndmask_b32_e32 v45, v212, v33, vcc
	v_max_f32_e32 v33, 0, v35
	v_add_u32_e32 v61, 0x7a, v81
	v_mul_f32_e32 v35, 0x3f317217, v36
	v_fma_f32 v35, v36, s83, -v35
	v_fmac_f32_e32 v35, 0x3377d1cf, v36
	v_fmac_f32_e32 v35, 0x3f317217, v36
	s_nop 1
	v_add_f32_e32 v33, v33, v35
	v_mul_f32_e32 v35, 0x3e000000, v47
	v_mul_f32_e64 v36, |v35|, s37
	v_exp_f32_e32 v36, v36
	v_cmp_lt_i32_e32 vcc, v61, v102
	v_add_f32_e32 v36, 1.0, v36
	v_cndmask_b32_e64 v123, 0, -v33, vcc
	v_fma_f32 v33, v46, s81, -v33
	v_log_f32_e32 v36, v36
	s_nop 0
	v_cndmask_b32_e32 v46, v212, v33, vcc
	v_max_f32_e32 v33, 0, v35
	v_mul_f32_e32 v35, 0x3f317217, v36
	v_fma_f32 v35, v36, s83, -v35
	v_fmac_f32_e32 v35, 0x3377d1cf, v36
	v_fmac_f32_e32 v35, 0x3f317217, v36
	s_nop 1
	v_add_f32_e32 v33, v33, v35
	v_add_u32_e32 v35, 0x7b, v81
	v_cmp_lt_i32_e32 vcc, v35, v102
	s_nop 1
	v_cndmask_b32_e64 v35, 0, -v33, vcc
	v_fma_f32 v33, v47, s81, -v33
	v_cndmask_b32_e32 v36, v212, v33, vcc
	v_add_f32_e32 v33, v85, v103
	v_add_f32_e32 v47, v106, v108
	v_add_f32_e32 v61, v33, v47
	v_add_f32_e32 v47, v121, v122
	v_add_f32_e32 v85, v123, v35
	v_add_f32_e32 v47, v47, v85
	ds_bpermute_b32 v85, v110, v47
	v_add_f32_e32 v121, v41, v120
	v_add_f32_e32 v37, v37, v121
	ds_bpermute_b32 v121, v110, v37
	ds_bpermute_b32 v33, v110, v61
	s_waitcnt lgkmcnt(0)
	v_cndmask_b32_e64 v124, 0, v85, s[52:53]
	v_add_f32_e32 v124, v63, v124
	v_add_f32_e32 v36, v124, v36
	v_mul_f32_e32 v36, 0x3fb8aa3b, v36
	v_add_f32_e32 v35, v124, v35
	v_exp_f32_e32 v125, v36
	v_add_f32_e32 v36, v46, v35
	v_mul_f32_e32 v36, 0x3fb8aa3b, v36
	v_add_f32_e32 v35, v123, v35
	v_exp_f32_e32 v124, v36
	v_add_f32_e32 v36, v45, v35
	v_add_f32_e32 v35, v122, v35
	v_add_f32_e32 v35, v44, v35
	v_mul_f32_e32 v35, 0x3fb8aa3b, v35
	v_mul_f32_e32 v36, 0x3fb8aa3b, v36
	v_exp_f32_e32 v122, v35
	v_add_f32_e32 v35, v47, v85
	v_exp_f32_e32 v46, v36
	v_add_f32_e32 v35, v63, v35
	v_cndmask_b32_e64 v36, 0, v121, s[52:53]
	v_add_f32_e32 v36, v36, v35
	v_add_f32_e32 v43, v43, v36
	v_add_f32_e32 v36, v120, v36
	v_add_f32_e32 v42, v42, v36
	v_add_f32_e32 v36, v41, v36
	v_add_f32_e32 v40, v40, v36
	v_add_f32_e32 v36, v39, v36
	v_add_f32_e32 v36, v38, v36
	v_mul_f32_e32 v36, 0x3fb8aa3b, v36
	v_add_f32_e32 v63, v37, v121
	v_exp_f32_e32 v85, v36
	v_pk_add_f32 v[36:37], v[62:63], v[34:35]
	v_pk_add_f32 v[38:39], v[60:61], v[32:33]
	v_mul_f32_e32 v40, 0x3fb8aa3b, v40
	v_pk_add_f32 v[38:39], v[38:39], v[36:37]
	v_exp_f32_e32 v44, v40
	v_cndmask_b32_e64 v40, 0, v33, s[52:53]
	ds_bpermute_b32 v33, v110, v38
	v_add_f32_e32 v35, v40, v37
	v_add_f32_e32 v36, v109, v35
	v_add_f32_e32 v35, v108, v35
	v_mul_f32_e32 v42, 0x3fb8aa3b, v42
	s_waitcnt lgkmcnt(0)
	v_cndmask_b32_e64 v41, 0, v33, s[52:53]
	v_add_f32_e32 v41, v41, v39
	v_add_f32_e32 v37, v107, v35
	v_add_f32_e32 v35, v106, v35
	v_add_f32_e32 v34, v34, v41
	v_exp_f32_e32 v47, v42
	v_add_f32_e32 v40, v105, v35
	v_add_f32_e32 v35, v103, v35
	v_add_f32_e32 v42, v87, v41
	v_add_f32_e32 v41, v86, v34
	v_add_f32_e32 v34, v62, v34
	v_mul_f32_e32 v43, 0x3fb8aa3b, v43
	v_add_f32_e32 v35, v99, v35
	v_add_f32_e32 v32, v32, v34
	v_exp_f32_e32 v45, v43
	v_mul_f32_e32 v40, 0x3fb8aa3b, v40
	v_mul_f32_e32 v35, 0x3fb8aa3b, v35
	v_mul_f32_e32 v42, 0x3fb8aa3b, v42
	v_mul_f32_e32 v41, 0x3fb8aa3b, v41
	v_add_f32_e32 v43, v84, v34
	v_add_f32_e32 v32, v83, v32
	v_mul_f32_e32 v36, 0x3fb8aa3b, v36
	v_mul_f32_e32 v37, 0x3fb8aa3b, v37
	v_exp_f32_e32 v40, v40
	v_exp_f32_e32 v35, v35
	v_exp_f32_e32 v42, v42
	v_mul_f32_e32 v43, 0x3fb8aa3b, v43
	v_mul_f32_e32 v32, 0x3fb8aa3b, v32
	v_exp_f32_e32 v34, v41
	v_exp_f32_e32 v36, v36
	v_exp_f32_e32 v37, v37
	v_exp_f32_e32 v43, v43
	v_exp_f32_e32 v32, v32
	v_add_f32_e32 v33, v38, v33
	v_add_f32_e32 v63, v33, v39
	v_cvt_pk_bf16_f32 v33, v34, v42
	v_cvt_pk_bf16_f32 v34, v35, v40
	v_cvt_pk_bf16_f32 v32, v32, v43
	v_cvt_pk_bf16_f32 v35, v37, v36
	v_cvt_pk_bf16_f32 v44, v85, v44
	v_cvt_pk_bf16_f32 v45, v47, v45
	v_cvt_pk_bf16_f32 v46, v122, v46
	v_cvt_pk_bf16_f32 v47, v124, v125
	s_waitcnt lgkmcnt(0)
	v_mfma_f32_32x32x16_bf16 v[16:31], v[180:183], v[32:35], v[16:31]
	v_mfma_f32_32x32x16_bf16 v[16:31], v[184:187], v[44:47], v[16:31]
	s_waitcnt lgkmcnt(0)
	v_mfma_f32_32x32x16_bf16 v[0:15], v[188:191], v[32:35], v[0:15]
	v_mfma_f32_32x32x16_bf16 v[0:15], v[192:195], v[44:47], v[0:15]
	v_cmp_gt_f32_e32 vcc, s5, v63
	s_cmp_lg_u64 vcc, exec
	s_cselect_b64 s[14:15], -1, 0
.LBB0_793:
	s_add_i32 s16, s6, 64
	s_cmp_le_i32 s16, s18
	s_cselect_b64 s[16:17], -1, 0
	s_and_b64 s[16:17], s[16:17], s[14:15]
	s_andn2_b64 vcc, exec, s[16:17]
	s_cbranch_vccnz .LBB0_795
	ds_read_b128 v[32:35], v82
	ds_read_b128 v[84:87], v82 offset:32
	ds_read_b128 v[106:109], v82 offset:64
	ds_read_b128 v[120:123], v82 offset:96
	s_waitcnt lgkmcnt(0)
	v_mfma_f32_32x32x16_bf16 v[32:47], v[32:35], v[64:67], 0
	v_mfma_f32_32x32x16_bf16 v[32:47], v[84:87], v[68:71], v[32:47]
	v_mfma_f32_32x32x16_bf16 v[32:47], v[106:109], v[72:75], v[32:47]
	v_mfma_f32_32x32x16_bf16 v[32:47], v[120:123], v[76:79], v[32:47]
	s_nop 10
	v_add_u32_e32 v197, 0x2000, v80
	ds_read2_b64 v[180:183], v197 offset0:128 offset1:130
	ds_read2_b64 v[184:187], v197 offset0:132 offset1:134
	v_add_u32_e32 v197, 0x3000, v80
	ds_read2_b64 v[188:191], v197 offset0:160 offset1:162
	ds_read2_b64 v[192:195], v197 offset0:164 offset1:166
	v_mul_f32_e32 v60, 0x3e000000, v32
	v_mul_f32_e64 v61, |v60|, s37
	v_exp_f32_e32 v61, v61
	v_mul_f32_e32 v83, 0x3e000000, v33
	v_add_u32_e32 v62, 64, v81
	v_max_f32_e32 v60, 0, v60
	v_add_f32_e32 v61, 1.0, v61
	s_nop 1
	v_log_f32_e32 v61, v61
	s_nop 0
	v_mul_f32_e32 v84, 0x3f317217, v61
	v_fma_f32 v84, v61, s83, -v84
	v_fmac_f32_e32 v84, 0x3377d1cf, v61
	v_fmac_f32_e32 v84, 0x3f317217, v61
	s_nop 1
	v_mov_b32_e32 v61, v84
	v_mul_f32_e64 v82, |v83|, s37
	v_exp_f32_e32 v82, v82
	v_cmp_lt_i32_e32 vcc, v62, v102
	v_add_f32_e32 v61, v60, v61
	v_fma_f32 v32, v32, s81, -v61
	v_add_f32_e32 v62, 1.0, v82
	v_cndmask_b32_e64 v60, 0, -v61, vcc
	s_nop 0
	v_log_f32_e32 v62, v62
	s_nop 0
	v_cndmask_b32_e32 v82, v212, v32, vcc
	v_max_f32_e32 v32, 0, v83
	v_mul_f32_e32 v61, 0x3f317217, v62
	v_fma_f32 v61, v62, s83, -v61
	v_fmac_f32_e32 v61, 0x3377d1cf, v62
	v_fmac_f32_e32 v61, 0x3f317217, v62
	s_nop 1
	v_mul_f32_e32 v62, 0x3e000000, v34
	v_add_f32_e32 v61, v32, v61
	v_mul_f32_e64 v32, |v62|, s37
	v_exp_f32_e32 v83, v32
	v_add_u32_e32 v32, 0x41, v81
	v_cmp_lt_i32_e32 vcc, v32, v102
	v_fma_f32 v33, v33, s81, -v61
	v_add_f32_e32 v83, 1.0, v83
	v_cndmask_b32_e64 v32, 0, -v61, vcc
	s_nop 0
	v_log_f32_e32 v84, v83
	s_nop 0
	v_cndmask_b32_e32 v83, v212, v33, vcc
	v_max_f32_e32 v33, 0, v62
	v_mul_f32_e32 v61, 0x3f317217, v84
	v_fma_f32 v61, v84, s83, -v61
	v_fmac_f32_e32 v61, 0x3377d1cf, v84
	v_fmac_f32_e32 v61, 0x3f317217, v84
	s_nop 1
	v_add_f32_e32 v33, v33, v61
	v_mul_f32_e32 v61, 0x3e000000, v35
	v_mul_f32_e64 v62, |v61|, s37
	v_exp_f32_e32 v84, v62
	v_add_u32_e32 v62, 0x42, v81
	v_cmp_lt_i32_e32 vcc, v62, v102
	v_add_f32_e32 v84, 1.0, v84
	v_cndmask_b32_e64 v62, 0, -v33, vcc
	v_fma_f32 v33, v34, s81, -v33
	v_log_f32_e32 v84, v84
	s_nop 0
	v_cndmask_b32_e32 v85, v212, v33, vcc
	v_max_f32_e32 v33, 0, v61
	v_mul_f32_e32 v34, 0x3f317217, v84
	v_fma_f32 v34, v84, s83, -v34
	v_fmac_f32_e32 v34, 0x3377d1cf, v84
	v_fmac_f32_e32 v34, 0x3f317217, v84
	s_nop 1
	v_mul_f32_e32 v61, 0x3e000000, v36
	v_add_f32_e32 v33, v33, v34
	v_mul_f32_e64 v34, |v61|, s37
	v_exp_f32_e32 v84, v34
	v_add_u32_e32 v34, 0x43, v81
	v_cmp_lt_i32_e32 vcc, v34, v102
	v_add_f32_e32 v84, 1.0, v84
	v_cndmask_b32_e64 v34, 0, -v33, vcc
	v_fma_f32 v33, v35, s81, -v33
	v_log_f32_e32 v84, v84
	s_nop 0
	v_cndmask_b32_e32 v86, v212, v33, vcc
	v_max_f32_e32 v33, 0, v61
	v_mul_f32_e32 v35, 0x3f317217, v84
	v_fma_f32 v35, v84, s83, -v35
	v_fmac_f32_e32 v35, 0x3377d1cf, v84
	v_fmac_f32_e32 v35, 0x3f317217, v84
	s_nop 1
	v_add_f32_e32 v33, v33, v35
	v_mul_f32_e32 v35, 0x3e000000, v37
	v_mul_f32_e64 v61, |v35|, s37
	v_exp_f32_e32 v61, v61
	v_add_u32_e32 v84, 0x48, v81
	v_cmp_lt_i32_e32 vcc, v84, v102
	v_add_f32_e32 v61, 1.0, v61
	v_cndmask_b32_e64 v84, 0, -v33, vcc
	v_fma_f32 v33, v36, s81, -v33
	v_log_f32_e32 v61, v61
	s_nop 0
	v_cndmask_b32_e32 v87, v212, v33, vcc
	v_max_f32_e32 v33, 0, v35
	v_mul_f32_e32 v35, 0x3f317217, v61
	v_fma_f32 v35, v61, s83, -v35
	v_fmac_f32_e32 v35, 0x3377d1cf, v61
	v_fmac_f32_e32 v35, 0x3f317217, v61
	s_nop 1
	v_add_f32_e32 v33, v33, v35
	v_mul_f32_e32 v35, 0x3e000000, v38
	v_mul_f32_e64 v36, |v35|, s37
	v_exp_f32_e32 v36, v36
	v_add_u32_e32 v61, 0x49, v81
	v_cmp_lt_i32_e32 vcc, v61, v102
	v_add_f32_e32 v36, 1.0, v36
	v_cndmask_b32_e64 v99, 0, -v33, vcc
	v_fma_f32 v33, v37, s81, -v33
	v_log_f32_e32 v36, v36
	s_nop 0
	v_cndmask_b32_e32 v103, v212, v33, vcc
	v_max_f32_e32 v33, 0, v35
	v_add_u32_e32 v37, 0x4a, v81
	v_mul_f32_e32 v35, 0x3f317217, v36
	v_fma_f32 v35, v36, s83, -v35
	v_fmac_f32_e32 v35, 0x3377d1cf, v36
	v_fmac_f32_e32 v35, 0x3f317217, v36
	s_nop 1
	v_add_f32_e32 v33, v33, v35
	v_mul_f32_e32 v35, 0x3e000000, v39
	v_mul_f32_e64 v36, |v35|, s37
	v_exp_f32_e32 v36, v36
	v_cmp_lt_i32_e32 vcc, v37, v102
	v_add_f32_e32 v36, 1.0, v36
	v_cndmask_b32_e64 v105, 0, -v33, vcc
	v_fma_f32 v33, v38, s81, -v33
	v_log_f32_e32 v36, v36
	s_nop 0
	v_cndmask_b32_e32 v106, v212, v33, vcc
	v_max_f32_e32 v33, 0, v35
	v_add_u32_e32 v37, 0x4b, v81
	v_mul_f32_e32 v35, 0x3f317217, v36
	v_fma_f32 v35, v36, s83, -v35
	v_fmac_f32_e32 v35, 0x3377d1cf, v36
	v_fmac_f32_e32 v35, 0x3f317217, v36
	s_nop 1
	v_add_f32_e32 v33, v33, v35
	v_mul_f32_e32 v35, 0x3e000000, v40
	v_mul_f32_e64 v36, |v35|, s37
	v_exp_f32_e32 v36, v36
	v_cmp_lt_i32_e32 vcc, v37, v102
	v_add_f32_e32 v36, 1.0, v36
	v_cndmask_b32_e64 v107, 0, -v33, vcc
	v_fma_f32 v33, v39, s81, -v33
	v_log_f32_e32 v36, v36
	s_nop 0
	v_cndmask_b32_e32 v108, v212, v33, vcc
	v_max_f32_e32 v33, 0, v35
	v_add_u32_e32 v37, 0x50, v81
	v_mul_f32_e32 v35, 0x3f317217, v36
	v_fma_f32 v35, v36, s83, -v35
	v_fmac_f32_e32 v35, 0x3377d1cf, v36
	v_fmac_f32_e32 v35, 0x3f317217, v36
	v_add_u32_e32 v39, 0x51, v81
	s_nop 0
	v_add_f32_e32 v33, v33, v35
	v_mul_f32_e32 v35, 0x3e000000, v41
	v_mul_f32_e64 v36, |v35|, s37
	v_exp_f32_e32 v36, v36
	v_cmp_lt_i32_e32 vcc, v37, v102
	v_add_f32_e32 v36, 1.0, v36
	v_cndmask_b32_e64 v37, 0, -v33, vcc
	v_fma_f32 v33, v40, s81, -v33
	v_log_f32_e32 v36, v36
	s_nop 0
	v_cndmask_b32_e32 v38, v212, v33, vcc
	v_max_f32_e32 v33, 0, v35
	v_mul_f32_e32 v35, 0x3f317217, v36
	v_fma_f32 v35, v36, s83, -v35
	v_fmac_f32_e32 v35, 0x3377d1cf, v36
	v_fmac_f32_e32 v35, 0x3f317217, v36
	s_nop 1
	v_add_f32_e32 v33, v33, v35
	v_mul_f32_e32 v35, 0x3e000000, v42
	v_mul_f32_e64 v36, |v35|, s37
	v_exp_f32_e32 v36, v36
	v_cmp_lt_i32_e32 vcc, v39, v102
	v_add_f32_e32 v36, 1.0, v36
	v_cndmask_b32_e64 v39, 0, -v33, vcc
	v_fma_f32 v33, v41, s81, -v33
	v_log_f32_e32 v36, v36
	s_nop 0
	v_cndmask_b32_e32 v40, v212, v33, vcc
	v_max_f32_e32 v33, 0, v35
	v_add_u32_e32 v41, 0x52, v81
	v_mul_f32_e32 v35, 0x3f317217, v36
	v_fma_f32 v35, v36, s83, -v35
	v_fmac_f32_e32 v35, 0x3377d1cf, v36
	v_fmac_f32_e32 v35, 0x3f317217, v36
	v_add_f32_e32 v37, v37, v39
	s_nop 0
	v_add_f32_e32 v33, v33, v35
	v_mul_f32_e32 v35, 0x3e000000, v43
	v_mul_f32_e64 v36, |v35|, s37
	v_exp_f32_e32 v36, v36
	v_cmp_lt_i32_e32 vcc, v41, v102
	v_add_f32_e32 v36, 1.0, v36
	v_cndmask_b32_e64 v41, 0, -v33, vcc
	v_fma_f32 v33, v42, s81, -v33
	v_log_f32_e32 v36, v36
	s_nop 0
	v_cndmask_b32_e32 v42, v212, v33, vcc
	v_max_f32_e32 v33, 0, v35
	v_add_u32_e32 v61, 0x53, v81
	v_mul_f32_e32 v35, 0x3f317217, v36
	v_fma_f32 v35, v36, s83, -v35
	v_fmac_f32_e32 v35, 0x3377d1cf, v36
	v_fmac_f32_e32 v35, 0x3f317217, v36
	s_nop 1
	v_add_f32_e32 v33, v33, v35
	v_mul_f32_e32 v35, 0x3e000000, v44
	v_mul_f32_e64 v36, |v35|, s37
	v_exp_f32_e32 v36, v36
	v_cmp_lt_i32_e32 vcc, v61, v102
	v_add_f32_e32 v36, 1.0, v36
	v_cndmask_b32_e64 v109, 0, -v33, vcc
	v_fma_f32 v33, v43, s81, -v33
	v_log_f32_e32 v36, v36
	s_nop 0
	v_cndmask_b32_e32 v43, v212, v33, vcc
	v_max_f32_e32 v33, 0, v35
	v_add_u32_e32 v61, 0x58, v81
	v_mul_f32_e32 v35, 0x3f317217, v36
	v_fma_f32 v35, v36, s83, -v35
	v_fmac_f32_e32 v35, 0x3377d1cf, v36
	v_fmac_f32_e32 v35, 0x3f317217, v36
	s_nop 1
	v_add_f32_e32 v33, v33, v35
	v_mul_f32_e32 v35, 0x3e000000, v45
	v_mul_f32_e64 v36, |v35|, s37
	v_exp_f32_e32 v36, v36
	v_cmp_lt_i32_e32 vcc, v61, v102
	v_add_f32_e32 v36, 1.0, v36
	v_cndmask_b32_e64 v120, 0, -v33, vcc
	v_fma_f32 v33, v44, s81, -v33
	v_log_f32_e32 v36, v36
	s_nop 0
	v_cndmask_b32_e32 v44, v212, v33, vcc
	v_max_f32_e32 v33, 0, v35
	v_add_u32_e32 v61, 0x59, v81
	v_mul_f32_e32 v35, 0x3f317217, v36
	v_fma_f32 v35, v36, s83, -v35
	v_fmac_f32_e32 v35, 0x3377d1cf, v36
	v_fmac_f32_e32 v35, 0x3f317217, v36
	s_nop 1
	v_add_f32_e32 v33, v33, v35
	v_mul_f32_e32 v35, 0x3e000000, v46
	v_mul_f32_e64 v36, |v35|, s37
	v_exp_f32_e32 v36, v36
	v_cmp_lt_i32_e32 vcc, v61, v102
	v_add_f32_e32 v36, 1.0, v36
	v_cndmask_b32_e64 v121, 0, -v33, vcc
	v_fma_f32 v33, v45, s81, -v33
	v_log_f32_e32 v36, v36
	s_nop 0
	v_cndmask_b32_e32 v45, v212, v33, vcc
	v_max_f32_e32 v33, 0, v35
	v_add_u32_e32 v61, 0x5a, v81
	v_mul_f32_e32 v35, 0x3f317217, v36
	v_fma_f32 v35, v36, s83, -v35
	v_fmac_f32_e32 v35, 0x3377d1cf, v36
	v_fmac_f32_e32 v35, 0x3f317217, v36
	s_nop 1
	v_add_f32_e32 v33, v33, v35
	v_mul_f32_e32 v35, 0x3e000000, v47
	v_mul_f32_e64 v36, |v35|, s37
	v_exp_f32_e32 v36, v36
	v_cmp_lt_i32_e32 vcc, v61, v102
	v_add_f32_e32 v36, 1.0, v36
	v_cndmask_b32_e64 v122, 0, -v33, vcc
	v_fma_f32 v33, v46, s81, -v33
	v_log_f32_e32 v36, v36
	s_nop 0
	v_cndmask_b32_e32 v46, v212, v33, vcc
	v_max_f32_e32 v33, 0, v35
	v_mul_f32_e32 v35, 0x3f317217, v36
	v_fma_f32 v35, v36, s83, -v35
	v_fmac_f32_e32 v35, 0x3377d1cf, v36
	v_fmac_f32_e32 v35, 0x3f317217, v36
	s_nop 1
	v_add_f32_e32 v33, v33, v35
	v_add_u32_e32 v35, 0x5b, v81
	v_cmp_lt_i32_e32 vcc, v35, v102
	s_nop 1
	v_cndmask_b32_e64 v35, 0, -v33, vcc
	v_fma_f32 v33, v47, s81, -v33
	v_cndmask_b32_e32 v36, v212, v33, vcc
	v_add_f32_e32 v33, v84, v99
	v_add_f32_e32 v47, v105, v107
	v_add_f32_e32 v61, v33, v47
	v_add_f32_e32 v47, v120, v121
	v_add_f32_e32 v81, v122, v35
	v_add_f32_e32 v47, v47, v81
	ds_bpermute_b32 v81, v110, v47
	v_add_f32_e32 v84, v41, v109
	v_add_f32_e32 v37, v37, v84
	ds_bpermute_b32 v84, v110, v37
	ds_bpermute_b32 v33, v110, v61
	s_waitcnt lgkmcnt(0)
	v_cndmask_b32_e64 v120, 0, v81, s[52:53]
	v_add_f32_e32 v120, v63, v120
	v_add_f32_e32 v36, v120, v36
	v_mul_f32_e32 v36, 0x3fb8aa3b, v36
	v_add_f32_e32 v35, v120, v35
	v_exp_f32_e32 v123, v36
	v_add_f32_e32 v36, v46, v35
	v_mul_f32_e32 v36, 0x3fb8aa3b, v36
	v_add_f32_e32 v35, v122, v35
	v_exp_f32_e32 v120, v36
	v_add_f32_e32 v36, v45, v35
	v_add_f32_e32 v35, v121, v35
	v_add_f32_e32 v35, v44, v35
	v_mul_f32_e32 v35, 0x3fb8aa3b, v35
	v_mul_f32_e32 v36, 0x3fb8aa3b, v36
	v_exp_f32_e32 v121, v35
	v_add_f32_e32 v35, v47, v81
	v_exp_f32_e32 v46, v36
	v_add_f32_e32 v35, v63, v35
	v_cndmask_b32_e64 v36, 0, v84, s[52:53]
	v_add_f32_e32 v36, v36, v35
	v_add_f32_e32 v43, v43, v36
	v_add_f32_e32 v36, v109, v36
	v_add_f32_e32 v42, v42, v36
	v_add_f32_e32 v36, v41, v36
	v_add_f32_e32 v40, v40, v36
	v_add_f32_e32 v36, v39, v36
	v_add_f32_e32 v36, v38, v36
	v_mul_f32_e32 v36, 0x3fb8aa3b, v36
	v_add_f32_e32 v63, v37, v84
	v_exp_f32_e32 v81, v36
	v_pk_add_f32 v[36:37], v[62:63], v[34:35]
	v_pk_add_f32 v[38:39], v[60:61], v[32:33]
	v_mul_f32_e32 v40, 0x3fb8aa3b, v40
	v_pk_add_f32 v[38:39], v[38:39], v[36:37]
	v_exp_f32_e32 v44, v40
	v_cndmask_b32_e64 v40, 0, v33, s[52:53]
	ds_bpermute_b32 v33, v110, v38
	v_add_f32_e32 v35, v40, v37
	v_add_f32_e32 v36, v108, v35
	v_add_f32_e32 v35, v107, v35
	v_mul_f32_e32 v42, 0x3fb8aa3b, v42
	s_waitcnt lgkmcnt(0)
	v_cndmask_b32_e64 v41, 0, v33, s[52:53]
	v_add_f32_e32 v41, v41, v39
	v_add_f32_e32 v37, v106, v35
	v_add_f32_e32 v35, v105, v35
	v_add_f32_e32 v34, v34, v41
	v_exp_f32_e32 v47, v42
	v_add_f32_e32 v40, v103, v35
	v_add_f32_e32 v35, v99, v35
	v_add_f32_e32 v42, v86, v41
	v_add_f32_e32 v41, v85, v34
	v_add_f32_e32 v34, v62, v34
	v_mul_f32_e32 v43, 0x3fb8aa3b, v43
	v_add_f32_e32 v35, v87, v35
	v_add_f32_e32 v32, v32, v34
	v_exp_f32_e32 v45, v43
	v_mul_f32_e32 v40, 0x3fb8aa3b, v40
	v_mul_f32_e32 v35, 0x3fb8aa3b, v35
	v_mul_f32_e32 v42, 0x3fb8aa3b, v42
	v_mul_f32_e32 v41, 0x3fb8aa3b, v41
	v_add_f32_e32 v43, v83, v34
	v_add_f32_e32 v32, v82, v32
	v_mul_f32_e32 v36, 0x3fb8aa3b, v36
	v_mul_f32_e32 v37, 0x3fb8aa3b, v37
	v_exp_f32_e32 v40, v40
	v_exp_f32_e32 v35, v35
	v_exp_f32_e32 v42, v42
	v_mul_f32_e32 v43, 0x3fb8aa3b, v43
	v_mul_f32_e32 v32, 0x3fb8aa3b, v32
	v_exp_f32_e32 v34, v41
	v_exp_f32_e32 v36, v36
	v_exp_f32_e32 v37, v37
	v_exp_f32_e32 v43, v43
	v_exp_f32_e32 v32, v32
	v_add_f32_e32 v33, v38, v33
	v_add_f32_e32 v63, v33, v39
	v_cvt_pk_bf16_f32 v33, v34, v42
	v_cvt_pk_bf16_f32 v34, v35, v40
	v_cvt_pk_bf16_f32 v32, v32, v43
	v_cvt_pk_bf16_f32 v35, v37, v36
	v_cvt_pk_bf16_f32 v44, v81, v44
	v_cvt_pk_bf16_f32 v45, v47, v45
	v_cvt_pk_bf16_f32 v46, v121, v46
	v_cvt_pk_bf16_f32 v47, v120, v123
	s_waitcnt lgkmcnt(0)
	v_mfma_f32_32x32x16_bf16 v[16:31], v[180:183], v[32:35], v[16:31]
	v_mfma_f32_32x32x16_bf16 v[16:31], v[184:187], v[44:47], v[16:31]
	s_waitcnt lgkmcnt(0)
	v_mfma_f32_32x32x16_bf16 v[0:15], v[188:191], v[32:35], v[0:15]
	v_mfma_f32_32x32x16_bf16 v[0:15], v[192:195], v[44:47], v[0:15]
	v_cmp_gt_f32_e32 vcc, s5, v63
	s_cmp_lg_u64 vcc, exec
	s_cselect_b64 s[14:15], -1, 0
